# GLA sample chains: hand-written sequential pass with LDS-staged operands (each chunk fetched once per workgroup, coalesced, one chunk ahead); chains pinned to distinct CUs; permlane max-reduction at a
# speedup vs baseline: 1.0180x; 1.0032x over previous
.LBB0_488:
	ds_read_b128 v[84:87], v123
	ds_read_b128 v[88:91], v123 offset:64
	ds_read_b128 v[92:95], v123 offset:2304
	ds_read_b128 v[100:103], v123 offset:2368
	ds_read_b128 v[104:107], v123 offset:4608
	ds_read_b128 v[112:115], v123 offset:4672
	ds_read_b128 v[128:131], v123 offset:6912
	ds_read_b128 v[136:139], v123 offset:6976
	s_waitcnt lgkmcnt(7)
	v_mfma_f32_16x16x32_bf16 v[96:99], v[84:87], v[4:7], 0
	v_mbcnt_hi_u32_b32 v0, -1, v214
	v_and_b32_e32 v3, 64, v0
	v_xor_b32_e32 v2, 16, v0
	v_mfma_f32_16x16x32_bf16 v[84:87], v[84:87], v[12:15], 0
	v_add_u32_e32 v3, 64, v3
	v_cmp_lt_i32_e32 vcc, v2, v3
	s_waitcnt lgkmcnt(6)
	v_mfma_f32_16x16x32_bf16 v[140:143], v[88:91], v[8:11], v[96:99]
	v_cndmask_b32_e32 v2, v0, v2, vcc
	v_mfma_f32_16x16x32_bf16 v[96:99], v[88:91], v[16:19], v[84:87]
	s_waitcnt lgkmcnt(5)
	v_mfma_f32_16x16x32_bf16 v[84:87], v[92:95], v[4:7], 0
	v_mfma_f32_16x16x32_bf16 v[88:91], v[92:95], v[12:15], 0
	s_waitcnt lgkmcnt(4)
	v_mfma_f32_16x16x32_bf16 v[108:111], v[100:103], v[8:11], v[84:87]
	v_mfma_f32_16x16x32_bf16 v[92:95], v[100:103], v[16:19], v[88:91]
	s_waitcnt lgkmcnt(3)
	v_mfma_f32_16x16x32_bf16 v[84:87], v[104:107], v[4:7], 0
	v_mfma_f32_16x16x32_bf16 v[88:91], v[104:107], v[12:15], 0
	s_waitcnt lgkmcnt(2)
	v_mfma_f32_16x16x32_bf16 v[104:107], v[112:115], v[8:11], v[84:87]
	v_mfma_f32_16x16x32_bf16 v[88:91], v[112:115], v[16:19], v[88:91]
	s_waitcnt lgkmcnt(1)
	v_mfma_f32_16x16x32_bf16 v[84:87], v[128:131], v[4:7], 0
	v_mfma_f32_16x16x32_bf16 v[112:115], v[128:131], v[12:15], 0
	s_waitcnt lgkmcnt(0)
	v_mfma_f32_16x16x32_bf16 v[100:103], v[136:139], v[8:11], v[84:87]
	v_mfma_f32_16x16x32_bf16 v[84:87], v[136:139], v[16:19], v[112:115]
	v_lshlrev_b32_e32 v136, 2, v2
	v_xor_b32_e32 v2, 32, v0
	v_cmp_lt_i32_e32 vcc, v2, v3
	v_mul_f32_e32 v3, 0x3e38aa3b, v143
	s_nop 0
	v_cndmask_b32_e32 v0, v0, v2, vcc
	v_lshlrev_b32_e32 v135, 2, v0
	v_mul_f32_e32 v0, 0x3e38aa3b, v140
	v_mul_f32_e32 v2, 0x3e38aa3b, v141
	v_max3_f32 v0, v0, s82, v2
	v_mul_f32_e32 v2, 0x3e38aa3b, v142
	v_max3_f32 v0, v0, v2, v3
	v_mul_f32_e32 v2, 0x3e38aa3b, v108
	v_mul_f32_e32 v3, 0x3e38aa3b, v109
	v_max3_f32 v0, v0, v2, v3
	v_mul_f32_e32 v2, 0x3e38aa3b, v110
	v_mul_f32_e32 v3, 0x3e38aa3b, v111
	v_max3_f32 v0, v0, v2, v3
	v_mul_f32_e32 v2, 0x3e38aa3b, v104
	v_mul_f32_e32 v3, 0x3e38aa3b, v105
	v_max3_f32 v0, v0, v2, v3
	v_mul_f32_e32 v2, 0x3e38aa3b, v106
	v_mul_f32_e32 v3, 0x3e38aa3b, v107
	v_max3_f32 v0, v0, v2, v3
	v_mul_f32_e32 v2, 0x3e38aa3b, v100
	v_mul_f32_e32 v3, 0x3e38aa3b, v101
	v_max3_f32 v0, v0, v2, v3
	v_mul_f32_e32 v2, 0x3e38aa3b, v102
	v_mul_f32_e32 v3, 0x3e38aa3b, v103
	v_max3_f32 v0, v0, v2, v3
	v_mov_b32_e32 v2, v0
	s_waitcnt lgkmcnt(0)
	s_nop 1
	v_permlane16_swap_b32_e32 v2, v0
	v_max_f32_e32 v0, v0, v2
	v_mov_b32_e32 v2, v0
	s_waitcnt lgkmcnt(0)
	s_nop 1
	v_permlane32_swap_b32_e32 v2, v0
	v_max3_f32 v128, v126, v0, v2
	v_fma_f32 v0, v140, s83, -v128
	v_exp_f32_e32 v0, v0
	v_fma_f32 v3, v141, s83, -v128
	v_exp_f32_e32 v137, v3
	v_fma_f32 v3, v142, s83, -v128
	v_exp_f32_e32 v138, v3
	v_fma_f32 v3, v143, s83, -v128
	v_exp_f32_e32 v139, v3
	v_fma_f32 v3, v108, s83, -v128
	v_add_f32_e32 v2, 0, v0
	v_exp_f32_e32 v140, v3
	v_fma_f32 v3, v109, s83, -v128
	v_add_f32_e32 v2, v137, v2
	v_exp_f32_e32 v141, v3
	v_fma_f32 v3, v110, s83, -v128
	v_add_f32_e32 v2, v138, v2
	v_exp_f32_e32 v142, v3
	v_fma_f32 v3, v111, s83, -v128
	v_add_f32_e32 v2, v139, v2
	v_exp_f32_e32 v143, v3
	v_fma_f32 v3, v104, s83, -v128
	v_add_f32_e32 v2, v140, v2
	v_exp_f32_e32 v144, v3
	v_fma_f32 v3, v105, s83, -v128
	v_add_f32_e32 v2, v141, v2
	v_exp_f32_e32 v145, v3
	v_fma_f32 v3, v106, s83, -v128
	v_add_f32_e32 v2, v142, v2
	v_exp_f32_e32 v146, v3
	v_fma_f32 v3, v107, s83, -v128
	v_add_f32_e32 v2, v143, v2
	v_exp_f32_e32 v147, v3
	v_fma_f32 v3, v100, s83, -v128
	v_add_f32_e32 v2, v144, v2
	v_exp_f32_e32 v148, v3
	v_fma_f32 v3, v101, s83, -v128
	v_add_f32_e32 v2, v145, v2
	v_exp_f32_e32 v149, v3
	v_fma_f32 v3, v102, s83, -v128
	v_add_f32_e32 v2, v146, v2
	v_exp_f32_e32 v150, v3
	v_fma_f32 v3, v103, s83, -v128
	v_add_f32_e32 v2, v147, v2
	v_exp_f32_e32 v151, v3
	v_add_f32_e32 v2, v148, v2
	v_add_f32_e32 v2, v149, v2
	v_add_f32_e32 v2, v150, v2
	v_cmp_gt_f32_e32 vcc, v128, v126
	v_add_f32_e32 v2, v151, v2
	s_cbranch_vccz .LBB0_504
	v_sub_f32_e32 v3, v126, v128
	v_exp_f32_e32 v112, v3
	v_mov_b32_e32 v129, v127
	v_mov_b32_e32 v131, v125
	v_fma_f32 v130, v124, v112, v2
	v_pk_mul_f32 v[102:103], v[82:83], v[112:113] op_sel_hi:[1,0]
	v_pk_mul_f32 v[100:101], v[80:81], v[112:113] op_sel_hi:[1,0]
	v_pk_mul_f32 v[106:107], v[78:79], v[112:113] op_sel_hi:[1,0]
	v_pk_mul_f32 v[104:105], v[76:77], v[112:113] op_sel_hi:[1,0]
	v_pk_mul_f32 v[110:111], v[74:75], v[112:113] op_sel_hi:[1,0]
	v_pk_mul_f32 v[108:109], v[72:73], v[112:113] op_sel_hi:[1,0]
	v_pk_mul_f32 v[114:115], v[70:71], v[112:113] op_sel_hi:[1,0]
	v_pk_mul_f32 v[112:113], v[68:69], v[112:113] op_sel_hi:[1,0]
	s_cbranch_execnz .LBB0_491

.LBB0_491:
	v_mul_f32_e32 v2, 0x3e38aa3b, v96
	v_mul_f32_e32 v3, 0x3e38aa3b, v97
	v_max3_f32 v2, v2, s82, v3
	v_mul_f32_e32 v3, 0x3e38aa3b, v98
	v_mul_f32_e32 v68, 0x3e38aa3b, v99
	v_max3_f32 v2, v2, v3, v68
	v_mul_f32_e32 v3, 0x3e38aa3b, v92
	v_mul_f32_e32 v68, 0x3e38aa3b, v93
	v_max3_f32 v2, v2, v3, v68
	v_mul_f32_e32 v3, 0x3e38aa3b, v94
	v_mul_f32_e32 v68, 0x3e38aa3b, v95
	v_max3_f32 v2, v2, v3, v68
	v_mul_f32_e32 v3, 0x3e38aa3b, v88
	v_mul_f32_e32 v68, 0x3e38aa3b, v89
	v_max3_f32 v2, v2, v3, v68
	v_mul_f32_e32 v3, 0x3e38aa3b, v90
	v_mul_f32_e32 v68, 0x3e38aa3b, v91
	v_max3_f32 v2, v2, v3, v68
	v_mul_f32_e32 v3, 0x3e38aa3b, v84
	v_mul_f32_e32 v68, 0x3e38aa3b, v85
	v_max3_f32 v2, v2, v3, v68
	v_mul_f32_e32 v3, 0x3e38aa3b, v86
	v_mul_f32_e32 v68, 0x3e38aa3b, v87
	v_max3_f32 v2, v2, v3, v68
	v_mov_b32_e32 v3, v2
	s_waitcnt lgkmcnt(0)
	s_nop 1
	v_permlane16_swap_b32_e32 v3, v2
	v_max_f32_e32 v2, v2, v3
	v_mov_b32_e32 v3, v2
	s_waitcnt lgkmcnt(0)
	s_nop 1
	v_permlane32_swap_b32_e32 v3, v2
	v_max3_f32 v3, v129, v2, v3
	v_fma_f32 v2, v96, s83, -v3
	v_exp_f32_e32 v96, v2
	v_fma_f32 v2, v97, s83, -v3
	v_exp_f32_e32 v97, v2
	v_fma_f32 v2, v98, s83, -v3
	v_exp_f32_e32 v98, v2
	v_fma_f32 v2, v99, s83, -v3
	v_exp_f32_e32 v99, v2
	v_fma_f32 v68, v92, s83, -v3
	v_add_f32_e32 v2, 0, v96
	v_exp_f32_e32 v92, v68
	v_fma_f32 v68, v93, s83, -v3
	v_add_f32_e32 v2, v97, v2
	v_exp_f32_e32 v93, v68
	v_fma_f32 v68, v94, s83, -v3
	v_add_f32_e32 v2, v98, v2
	v_exp_f32_e32 v94, v68
	v_fma_f32 v68, v95, s83, -v3
	v_add_f32_e32 v2, v99, v2
	v_exp_f32_e32 v95, v68
	v_fma_f32 v68, v88, s83, -v3
	v_add_f32_e32 v2, v92, v2
	v_exp_f32_e32 v88, v68
	v_fma_f32 v68, v89, s83, -v3
	v_add_f32_e32 v2, v93, v2
	v_exp_f32_e32 v89, v68
	v_fma_f32 v68, v90, s83, -v3
	v_add_f32_e32 v2, v94, v2
	v_exp_f32_e32 v90, v68
	v_fma_f32 v68, v91, s83, -v3
	v_add_f32_e32 v2, v95, v2
	v_exp_f32_e32 v91, v68
	v_fma_f32 v68, v84, s83, -v3
	v_add_f32_e32 v2, v88, v2
	v_exp_f32_e32 v84, v68
	v_fma_f32 v68, v85, s83, -v3
	v_add_f32_e32 v2, v89, v2
	v_exp_f32_e32 v85, v68
	v_fma_f32 v68, v86, s83, -v3
	v_add_f32_e32 v2, v90, v2
	v_exp_f32_e32 v86, v68
	v_fma_f32 v68, v87, s83, -v3
	v_add_f32_e32 v2, v91, v2
	v_exp_f32_e32 v87, v68
	v_add_f32_e32 v2, v84, v2
	v_add_f32_e32 v2, v85, v2
	v_add_f32_e32 v2, v86, v2
	v_cmp_gt_f32_e32 vcc, v3, v129
	v_add_f32_e32 v126, v87, v2
	s_cbranch_vccz .LBB0_505
	v_sub_f32_e32 v2, v129, v3
	v_exp_f32_e32 v80, v2
	v_mov_b32_e32 v2, v128
	v_mov_b32_e32 v124, v130
	v_fma_f32 v125, v131, v80, v126
	v_pk_mul_f32 v[70:71], v[66:67], v[80:81] op_sel_hi:[1,0]
	v_pk_mul_f32 v[68:69], v[64:65], v[80:81] op_sel_hi:[1,0]
	v_pk_mul_f32 v[74:75], v[62:63], v[80:81] op_sel_hi:[1,0]
	v_pk_mul_f32 v[72:73], v[60:61], v[80:81] op_sel_hi:[1,0]
	v_pk_mul_f32 v[78:79], v[58:59], v[80:81] op_sel_hi:[1,0]
	v_pk_mul_f32 v[76:77], v[56:57], v[80:81] op_sel_hi:[1,0]
	v_pk_mul_f32 v[82:83], v[54:55], v[80:81] op_sel_hi:[1,0]
	v_pk_mul_f32 v[80:81], v[52:53], v[80:81] op_sel_hi:[1,0]
	s_cbranch_execnz .LBB0_494

.LBB0_496:
	ds_read_b128 v[84:87], v123 offset:18432
	ds_read_b128 v[88:91], v123 offset:18496
	ds_read_b128 v[92:95], v123 offset:20736
	ds_read_b128 v[100:103], v123 offset:20800
	ds_read_b128 v[104:107], v123 offset:23040
	ds_read_b128 v[108:111], v123 offset:23104
	ds_read_b128 v[112:115], v123 offset:25344
	ds_read_b128 v[126:129], v123 offset:25408
	s_waitcnt lgkmcnt(7)
	v_mfma_f32_16x16x32_bf16 v[96:99], v[84:87], v[4:7], 0
	v_mfma_f32_16x16x32_bf16 v[84:87], v[84:87], v[12:15], 0
	s_waitcnt lgkmcnt(6)
	v_mfma_f32_16x16x32_bf16 v[138:141], v[88:91], v[8:11], v[96:99]
	v_mfma_f32_16x16x32_bf16 v[96:99], v[88:91], v[16:19], v[84:87]
	s_waitcnt lgkmcnt(5)
	v_mfma_f32_16x16x32_bf16 v[84:87], v[92:95], v[4:7], 0
	s_nop 4
	v_mul_f32_e32 v0, 0x3e38aa3b, v138
	v_mfma_f32_16x16x32_bf16 v[88:91], v[92:95], v[12:15], 0
	s_waitcnt lgkmcnt(4)
	v_mfma_f32_16x16x32_bf16 v[142:145], v[100:103], v[8:11], v[84:87]
	v_mfma_f32_16x16x32_bf16 v[92:95], v[100:103], v[16:19], v[88:91]
	s_waitcnt lgkmcnt(3)
	v_mfma_f32_16x16x32_bf16 v[84:87], v[104:107], v[4:7], 0
	v_mfma_f32_16x16x32_bf16 v[88:91], v[104:107], v[12:15], 0
	s_waitcnt lgkmcnt(2)
	v_mfma_f32_16x16x32_bf16 v[104:107], v[108:111], v[8:11], v[84:87]
	v_mfma_f32_16x16x32_bf16 v[88:91], v[108:111], v[16:19], v[88:91]
	s_waitcnt lgkmcnt(1)
	v_mfma_f32_16x16x32_bf16 v[84:87], v[112:115], v[4:7], 0
	v_mfma_f32_16x16x32_bf16 v[108:111], v[112:115], v[12:15], 0
	s_waitcnt lgkmcnt(0)
	v_mfma_f32_16x16x32_bf16 v[100:103], v[126:129], v[8:11], v[84:87]
	v_mfma_f32_16x16x32_bf16 v[84:87], v[126:129], v[16:19], v[108:111]
	s_nop 4
	v_mul_f32_e32 v108, 0x3e38aa3b, v139
	v_max3_f32 v0, v0, s82, v108
	v_mul_f32_e32 v108, 0x3e38aa3b, v140
	v_mul_f32_e32 v109, 0x3e38aa3b, v141
	v_max3_f32 v0, v0, v108, v109
	v_mul_f32_e32 v108, 0x3e38aa3b, v142
	v_mul_f32_e32 v109, 0x3e38aa3b, v143
	v_max3_f32 v0, v0, v108, v109
	v_mul_f32_e32 v108, 0x3e38aa3b, v144
	v_mul_f32_e32 v109, 0x3e38aa3b, v145
	v_max3_f32 v0, v0, v108, v109
	v_mul_f32_e32 v108, 0x3e38aa3b, v104
	v_mul_f32_e32 v109, 0x3e38aa3b, v105
	v_max3_f32 v0, v0, v108, v109
	v_mul_f32_e32 v108, 0x3e38aa3b, v106
	v_mul_f32_e32 v109, 0x3e38aa3b, v107
	v_max3_f32 v0, v0, v108, v109
	v_mul_f32_e32 v108, 0x3e38aa3b, v100
	v_mul_f32_e32 v109, 0x3e38aa3b, v101
	v_max3_f32 v0, v0, v108, v109
	v_mul_f32_e32 v108, 0x3e38aa3b, v102
	v_mul_f32_e32 v109, 0x3e38aa3b, v103
	v_max3_f32 v0, v0, v108, v109
	v_mov_b32_e32 v108, v0
	s_waitcnt lgkmcnt(0)
	s_nop 1
	v_permlane16_swap_b32_e32 v108, v0
	v_max_f32_e32 v0, v0, v108
	v_mov_b32_e32 v108, v0
	s_waitcnt lgkmcnt(0)
	s_nop 1
	v_permlane32_swap_b32_e32 v108, v0
	v_max3_f32 v128, v2, v0, v108
	v_fma_f32 v0, v138, s83, -v128
	v_exp_f32_e32 v0, v0
	v_fma_f32 v109, v139, s83, -v128
	v_exp_f32_e32 v137, v109
	v_fma_f32 v109, v140, s83, -v128
	v_exp_f32_e32 v138, v109
	v_fma_f32 v109, v141, s83, -v128
	v_exp_f32_e32 v139, v109
	v_fma_f32 v109, v142, s83, -v128
	v_add_f32_e32 v108, 0, v0
	v_exp_f32_e32 v140, v109
	v_fma_f32 v109, v143, s83, -v128
	v_add_f32_e32 v108, v137, v108
	v_exp_f32_e32 v141, v109
	v_fma_f32 v109, v144, s83, -v128
	v_add_f32_e32 v108, v138, v108
	v_exp_f32_e32 v142, v109
	v_fma_f32 v109, v145, s83, -v128
	v_add_f32_e32 v108, v139, v108
	v_exp_f32_e32 v143, v109
	v_fma_f32 v104, v104, s83, -v128
	v_add_f32_e32 v108, v140, v108
	v_exp_f32_e32 v144, v104
	v_fma_f32 v105, v105, s83, -v128
	v_add_f32_e32 v108, v141, v108
	v_exp_f32_e32 v145, v105
	v_fma_f32 v105, v106, s83, -v128
	v_add_f32_e32 v108, v142, v108
	v_exp_f32_e32 v146, v105
	v_fma_f32 v105, v107, s83, -v128
	v_add_f32_e32 v108, v143, v108
	v_exp_f32_e32 v147, v105
	v_fma_f32 v100, v100, s83, -v128
	v_add_f32_e32 v104, v144, v108
	v_exp_f32_e32 v148, v100
	v_fma_f32 v101, v101, s83, -v128
	v_add_f32_e32 v104, v145, v104
	v_exp_f32_e32 v149, v101
	v_fma_f32 v101, v102, s83, -v128
	v_add_f32_e32 v104, v146, v104
	v_exp_f32_e32 v150, v101
	v_fma_f32 v101, v103, s83, -v128
	v_add_f32_e32 v104, v147, v104
	v_exp_f32_e32 v151, v101
	v_add_f32_e32 v100, v148, v104
	v_add_f32_e32 v100, v149, v100
	v_add_f32_e32 v100, v150, v100
	v_cmp_gt_f32_e32 vcc, v128, v2
	v_add_f32_e32 v126, v151, v100
	s_cbranch_vccz .LBB0_506
	v_sub_f32_e32 v100, v2, v128
	v_exp_f32_e32 v112, v100
	v_mov_b32_e32 v129, v3
	v_mov_b32_e32 v131, v125
	v_fma_f32 v130, v124, v112, v126
	v_pk_mul_f32 v[102:103], v[70:71], v[112:113] op_sel_hi:[1,0]
	v_pk_mul_f32 v[100:101], v[68:69], v[112:113] op_sel_hi:[1,0]
	v_pk_mul_f32 v[106:107], v[74:75], v[112:113] op_sel_hi:[1,0]
	v_pk_mul_f32 v[104:105], v[72:73], v[112:113] op_sel_hi:[1,0]
	v_pk_mul_f32 v[110:111], v[78:79], v[112:113] op_sel_hi:[1,0]
	v_pk_mul_f32 v[108:109], v[76:77], v[112:113] op_sel_hi:[1,0]
	v_pk_mul_f32 v[114:115], v[82:83], v[112:113] op_sel_hi:[1,0]
	v_pk_mul_f32 v[112:113], v[80:81], v[112:113] op_sel_hi:[1,0]
	s_cbranch_execnz .LBB0_499

.LBB0_499:
	v_mul_f32_e32 v2, 0x3e38aa3b, v96
	v_mul_f32_e32 v3, 0x3e38aa3b, v97
	v_max3_f32 v2, v2, s82, v3
	v_mul_f32_e32 v3, 0x3e38aa3b, v98
	v_mul_f32_e32 v68, 0x3e38aa3b, v99
	v_max3_f32 v2, v2, v3, v68
	v_mul_f32_e32 v3, 0x3e38aa3b, v92
	v_mul_f32_e32 v68, 0x3e38aa3b, v93
	v_max3_f32 v2, v2, v3, v68
	v_mul_f32_e32 v3, 0x3e38aa3b, v94
	v_mul_f32_e32 v68, 0x3e38aa3b, v95
	v_max3_f32 v2, v2, v3, v68
	v_mul_f32_e32 v3, 0x3e38aa3b, v88
	v_mul_f32_e32 v68, 0x3e38aa3b, v89
	v_max3_f32 v2, v2, v3, v68
	v_mul_f32_e32 v3, 0x3e38aa3b, v90
	v_mul_f32_e32 v68, 0x3e38aa3b, v91
	v_max3_f32 v2, v2, v3, v68
	v_mul_f32_e32 v3, 0x3e38aa3b, v84
	v_mul_f32_e32 v68, 0x3e38aa3b, v85
	v_max3_f32 v2, v2, v3, v68
	v_mul_f32_e32 v3, 0x3e38aa3b, v86
	v_mul_f32_e32 v68, 0x3e38aa3b, v87
	v_max3_f32 v2, v2, v3, v68
	v_mov_b32_e32 v3, v2
	s_waitcnt lgkmcnt(0)
	s_nop 1
	v_permlane16_swap_b32_e32 v3, v2
	v_max_f32_e32 v2, v2, v3
	v_mov_b32_e32 v3, v2
	s_waitcnt lgkmcnt(0)
	s_nop 1
	v_permlane32_swap_b32_e32 v3, v2
	v_max3_f32 v127, v129, v2, v3
	v_fma_f32 v2, v96, s83, -v127
	v_exp_f32_e32 v2, v2
	v_fma_f32 v3, v97, s83, -v127
	v_exp_f32_e32 v3, v3
	v_fma_f32 v68, v98, s83, -v127
	v_exp_f32_e32 v96, v68
	v_fma_f32 v68, v99, s83, -v127
	v_exp_f32_e32 v97, v68
	v_fma_f32 v69, v92, s83, -v127
	v_add_f32_e32 v68, 0, v2
	v_exp_f32_e32 v92, v69
	v_fma_f32 v69, v93, s83, -v127
	v_add_f32_e32 v68, v3, v68
	v_exp_f32_e32 v93, v69
	v_fma_f32 v69, v94, s83, -v127
	v_add_f32_e32 v68, v96, v68
	v_exp_f32_e32 v94, v69
	v_fma_f32 v69, v95, s83, -v127
	v_add_f32_e32 v68, v97, v68
	v_exp_f32_e32 v95, v69
	v_fma_f32 v69, v88, s83, -v127
	v_add_f32_e32 v68, v92, v68
	v_exp_f32_e32 v88, v69
	v_fma_f32 v69, v89, s83, -v127
	v_add_f32_e32 v68, v93, v68
	v_exp_f32_e32 v89, v69
	v_fma_f32 v69, v90, s83, -v127
	v_add_f32_e32 v68, v94, v68
	v_exp_f32_e32 v90, v69
	v_fma_f32 v69, v91, s83, -v127
	v_add_f32_e32 v68, v95, v68
	v_exp_f32_e32 v91, v69
	v_fma_f32 v69, v84, s83, -v127
	v_add_f32_e32 v68, v88, v68
	v_exp_f32_e32 v84, v69
	v_fma_f32 v69, v85, s83, -v127
	v_add_f32_e32 v68, v89, v68
	v_exp_f32_e32 v85, v69
	v_fma_f32 v69, v86, s83, -v127
	v_add_f32_e32 v68, v90, v68
	v_exp_f32_e32 v86, v69
	v_fma_f32 v69, v87, s83, -v127
	v_add_f32_e32 v68, v91, v68
	v_exp_f32_e32 v87, v69
	v_add_f32_e32 v68, v84, v68
	v_add_f32_e32 v68, v85, v68
	v_add_f32_e32 v68, v86, v68
	v_cmp_gt_f32_e32 vcc, v127, v129
	v_add_f32_e32 v98, v87, v68
	s_cbranch_vccz .LBB0_507
	v_sub_f32_e32 v68, v129, v127
	v_exp_f32_e32 v80, v68
	v_mov_b32_e32 v126, v128
	v_mov_b32_e32 v124, v130
	v_fma_f32 v125, v131, v80, v98
	v_pk_mul_f32 v[70:71], v[54:55], v[80:81] op_sel_hi:[1,0]
	v_pk_mul_f32 v[68:69], v[52:53], v[80:81] op_sel_hi:[1,0]
	v_pk_mul_f32 v[74:75], v[58:59], v[80:81] op_sel_hi:[1,0]
	v_pk_mul_f32 v[72:73], v[56:57], v[80:81] op_sel_hi:[1,0]
	v_pk_mul_f32 v[78:79], v[62:63], v[80:81] op_sel_hi:[1,0]
	v_pk_mul_f32 v[76:77], v[60:61], v[80:81] op_sel_hi:[1,0]
	v_pk_mul_f32 v[82:83], v[66:67], v[80:81] op_sel_hi:[1,0]
	v_pk_mul_f32 v[80:81], v[64:65], v[80:81] op_sel_hi:[1,0]
	s_cbranch_execnz .LBB0_502

.LBB0_556:
	ds_read_b128 v[84:87], v123
	ds_read_b128 v[88:91], v123 offset:64
	ds_read_b128 v[92:95], v123 offset:2304
	ds_read_b128 v[100:103], v123 offset:2368
	ds_read_b128 v[104:107], v123 offset:4608
	ds_read_b128 v[108:111], v123 offset:4672
	ds_read_b128 v[112:115], v123 offset:6912
	ds_read_b128 v[134:137], v123 offset:6976
	s_add_i32 s8, s19, -3
	s_cmp_lt_i32 s8, s13
	s_cselect_b64 s[8:9], -1, 0
	s_and_b64 s[40:41], s[8:9], exec
	s_cselect_b32 s40, 0, s13
	s_cselect_b32 s41, s76, 0x1000
	s_waitcnt lgkmcnt(7)
	v_mfma_f32_16x16x32_bf16 v[96:99], v[84:87], v[12:15], 0
	s_lshl_b32 s40, s40, 6
	v_and_b32_e32 v0, 64, v215
	s_sub_i32 s40, s40, s41
	v_mfma_f32_16x16x32_bf16 v[84:87], v[84:87], v[20:23], 0
	v_add_u32_e32 v149, s40, v133
	v_add_u32_e32 v2, 0x73, v149
	v_sub_u32_e32 v3, 0xffffff8d, v149
	s_waitcnt lgkmcnt(6)
	v_mfma_f32_16x16x32_bf16 v[140:143], v[88:91], v[16:19], v[96:99]
	v_max_i32_e32 v2, v2, v3
	v_add_u32_e32 v3, 0x72, v149
	v_mfma_f32_16x16x32_bf16 v[96:99], v[88:91], v[24:27], v[84:87]
	s_waitcnt lgkmcnt(5)
	v_mfma_f32_16x16x32_bf16 v[84:87], v[92:95], v[12:15], 0
	v_mfma_f32_16x16x32_bf16 v[88:91], v[92:95], v[20:23], 0
	s_waitcnt lgkmcnt(4)
	v_mfma_f32_16x16x32_bf16 v[144:147], v[100:103], v[16:19], v[84:87]
	v_mfma_f32_16x16x32_bf16 v[92:95], v[100:103], v[24:27], v[88:91]
	s_waitcnt lgkmcnt(3)
	v_mfma_f32_16x16x32_bf16 v[84:87], v[104:107], v[12:15], 0
	v_mfma_f32_16x16x32_bf16 v[88:91], v[104:107], v[20:23], 0
	s_waitcnt lgkmcnt(2)
	v_mfma_f32_16x16x32_bf16 v[104:107], v[108:111], v[16:19], v[84:87]
	v_mfma_f32_16x16x32_bf16 v[88:91], v[108:111], v[24:27], v[88:91]
	s_waitcnt lgkmcnt(1)
	v_mfma_f32_16x16x32_bf16 v[84:87], v[112:115], v[12:15], 0
	s_nop 4
	v_mul_f32_e32 v104, 0x3e38aa3b, v104
	v_mul_f32_e32 v105, 0x3e38aa3b, v105
	v_mul_f32_e32 v106, 0x3e38aa3b, v106
	v_mfma_f32_16x16x32_bf16 v[108:111], v[112:115], v[20:23], 0
	v_sub_u32_e32 v112, 0xffffff9d, v149
	v_sub_u32_e32 v113, 0xffffff9e, v149
	v_sub_u32_e32 v114, 0xffffff9f, v149
	s_waitcnt lgkmcnt(0)
	v_mfma_f32_16x16x32_bf16 v[100:103], v[134:137], v[16:19], v[84:87]
	v_sub_u32_e32 v115, 0xffffffa0, v149
	v_mul_f32_e32 v107, 0x3e38aa3b, v107
	v_mfma_f32_16x16x32_bf16 v[84:87], v[134:137], v[24:27], v[108:111]
	v_xor_b32_e32 v135, 16, v215
	v_add_u32_e32 v134, 64, v0
	v_cmp_lt_i32_e32 vcc, v135, v134
	v_xor_b32_e32 v136, 32, v215
	v_sub_u32_e32 v108, 0xffffff8e, v149
	v_cndmask_b32_e32 v0, v215, v135, vcc
	v_cmp_lt_i32_e32 vcc, v136, v134
	v_lshlrev_b32_e32 v137, 2, v0
	v_max_i32_e32 v3, v3, v108
	v_cndmask_b32_e32 v0, v215, v136, vcc
	v_cmp_lt_u32_e32 vcc, s65, v2
	v_add_u32_e32 v109, 0x71, v149
	v_sub_u32_e32 v110, 0xffffff8f, v149
	s_and_b64 s[40:41], s[8:9], vcc
	v_cmp_lt_u32_e32 vcc, s65, v3
	v_max_i32_e32 v109, v109, v110
	v_add_u32_e32 v110, 0x70, v149
	v_sub_u32_e32 v111, 0xffffff90, v149
	s_and_b64 s[42:43], s[8:9], vcc
	v_cmp_lt_u32_e32 vcc, s65, v109
	v_max_i32_e32 v110, v110, v111
	v_add_u32_e32 v111, 0x63, v149
	s_and_b64 s[44:45], s[8:9], vcc
	v_cmp_lt_u32_e32 vcc, s65, v110
	v_max_i32_e32 v111, v111, v112
	v_add_u32_e32 v112, 0x62, v149
	s_and_b64 s[46:47], s[8:9], vcc
	v_cmp_lt_u32_e32 vcc, s65, v111
	v_max_i32_e32 v112, v112, v113
	v_add_u32_e32 v113, 0x61, v149
	s_and_b64 s[48:49], s[8:9], vcc
	v_cmp_lt_u32_e32 vcc, s65, v112
	v_max_i32_e32 v113, v113, v114
	v_add_u32_e32 v114, 0x60, v149
	s_and_b64 s[50:51], s[8:9], vcc
	v_cmp_lt_u32_e32 vcc, s65, v113
	v_max_i32_e32 v114, v114, v115
	s_and_b64 s[52:53], s[8:9], vcc
	v_cmp_lt_u32_e32 vcc, s65, v114
	v_add_u32_e32 v114, 0x53, v149
	v_sub_u32_e32 v115, 0xffffffad, v149
	v_max_i32_e32 v114, v114, v115
	s_and_b64 s[54:55], s[8:9], vcc
	v_cmp_lt_u32_e32 vcc, s65, v114
	v_add_u32_e32 v114, 0x52, v149
	v_sub_u32_e32 v115, 0xffffffae, v149
	v_max_i32_e32 v114, v114, v115
	s_and_b64 s[56:57], s[8:9], vcc
	v_cmp_lt_u32_e32 vcc, s65, v114
	v_add_u32_e32 v114, 0x51, v149
	v_sub_u32_e32 v115, 0xffffffaf, v149
	v_max_i32_e32 v114, v114, v115
	s_and_b64 s[58:59], s[8:9], vcc
	v_cmp_lt_u32_e32 vcc, s65, v114
	v_add_u32_e32 v114, 0x50, v149
	v_sub_u32_e32 v115, 0xffffffb0, v149
	v_max_i32_e32 v114, v114, v115
	s_and_b64 s[60:61], s[8:9], vcc
	v_cmp_lt_u32_e32 vcc, s65, v114
	v_add_u32_e32 v114, 0x43, v149
	v_sub_u32_e32 v115, 0xffffffbd, v149
	v_max_i32_e32 v114, v114, v115
	v_lshlrev_b32_e32 v138, 2, v0
	v_mul_f32_e32 v0, 0x3e38aa3b, v140
	v_mul_f32_e32 v2, 0x3e38aa3b, v141
	s_and_b64 s[62:63], s[8:9], vcc
	v_cmp_lt_u32_e32 vcc, s65, v114
	v_add_u32_e32 v114, 0x42, v149
	v_sub_u32_e32 v115, 0xffffffbe, v149
	v_cndmask_b32_e64 v0, v0, v221, s[40:41]
	v_cndmask_b32_e64 v3, v2, v221, s[42:43]
	v_mul_f32_e32 v108, 0x3e38aa3b, v142
	v_mul_f32_e32 v109, 0x3e38aa3b, v143
	v_mul_f32_e32 v100, 0x3e38aa3b, v100
	s_and_b64 vcc, s[8:9], vcc
	v_max_i32_e32 v114, v114, v115
	v_max3_f32 v2, v0, s82, v3
	v_cndmask_b32_e64 v108, v108, v221, s[44:45]
	v_cndmask_b32_e64 v109, v109, v221, s[46:47]
	v_mul_f32_e32 v110, 0x3e38aa3b, v144
	v_mul_f32_e32 v111, 0x3e38aa3b, v145
	v_cndmask_b32_e32 v100, v100, v221, vcc
	v_cmp_lt_u32_e32 vcc, s65, v114
	v_add_u32_e32 v114, 0x41, v149
	v_sub_u32_e32 v115, 0xffffffbf, v149
	v_max3_f32 v2, v2, v108, v109
	v_cndmask_b32_e64 v110, v110, v221, s[48:49]
	v_cndmask_b32_e64 v111, v111, v221, s[50:51]
	v_mul_f32_e32 v112, 0x3e38aa3b, v146
	v_mul_f32_e32 v113, 0x3e38aa3b, v147
	v_mul_f32_e32 v101, 0x3e38aa3b, v101
	s_and_b64 vcc, s[8:9], vcc
	v_max_i32_e32 v114, v114, v115
	v_max3_f32 v2, v2, v110, v111
	v_cndmask_b32_e64 v112, v112, v221, s[52:53]
	v_cndmask_b32_e64 v113, v113, v221, s[54:55]
	v_cndmask_b32_e32 v101, v101, v221, vcc
	v_cmp_lt_u32_e32 vcc, s65, v114
	v_add_u32_e32 v114, 64, v149
	v_sub_u32_e32 v115, 0xffffffc0, v149
	v_max3_f32 v2, v2, v112, v113
	v_cndmask_b32_e64 v104, v104, v221, s[56:57]
	v_cndmask_b32_e64 v105, v105, v221, s[58:59]
	v_mul_f32_e32 v102, 0x3e38aa3b, v102
	s_and_b64 vcc, s[8:9], vcc
	v_max_i32_e32 v114, v114, v115
	v_max3_f32 v2, v2, v104, v105
	v_cndmask_b32_e64 v106, v106, v221, s[60:61]
	v_cndmask_b32_e64 v107, v107, v221, s[62:63]
	v_cndmask_b32_e32 v102, v102, v221, vcc
	v_cmp_lt_u32_e32 vcc, s65, v114
	v_max3_f32 v2, v2, v106, v107
	v_mul_f32_e32 v103, 0x3e38aa3b, v103
	s_and_b64 vcc, s[8:9], vcc
	v_max3_f32 v2, v2, v100, v101
	v_cndmask_b32_e32 v103, v103, v221, vcc
	v_max3_f32 v2, v2, v102, v103
	v_mov_b32_e32 v114, v2
	s_waitcnt lgkmcnt(0)
	s_nop 1
	v_permlane16_swap_b32_e32 v114, v2
	v_max_f32_e32 v2, v2, v114
	v_mov_b32_e32 v114, v2
	s_waitcnt lgkmcnt(0)
	s_nop 1
	v_permlane32_swap_b32_e32 v114, v2
	v_max3_f32 v2, v126, v2, v114
	v_sub_f32_e32 v0, v0, v2
	v_exp_f32_e32 v0, v0
	v_sub_f32_e32 v3, v3, v2
	v_exp_f32_e32 v139, v3
	v_sub_f32_e32 v108, v108, v2
	v_exp_f32_e32 v140, v108
	v_sub_f32_e32 v108, v109, v2
	v_exp_f32_e32 v141, v108
	v_sub_f32_e32 v108, v110, v2
	v_add_f32_e32 v114, 0, v0
	v_exp_f32_e32 v142, v108
	v_sub_f32_e32 v108, v111, v2
	v_add_f32_e32 v3, v139, v114
	v_exp_f32_e32 v143, v108
	v_sub_f32_e32 v108, v112, v2
	v_add_f32_e32 v3, v140, v3
	v_exp_f32_e32 v144, v108
	v_sub_f32_e32 v108, v113, v2
	v_add_f32_e32 v3, v141, v3
	v_exp_f32_e32 v145, v108
	v_sub_f32_e32 v104, v104, v2
	v_add_f32_e32 v3, v142, v3
	v_exp_f32_e32 v146, v104
	v_sub_f32_e32 v104, v105, v2
	v_add_f32_e32 v3, v143, v3
	v_exp_f32_e32 v147, v104
	v_sub_f32_e32 v104, v106, v2
	v_add_f32_e32 v3, v144, v3
	v_exp_f32_e32 v148, v104
	v_sub_f32_e32 v104, v107, v2
	v_add_f32_e32 v3, v145, v3
	v_exp_f32_e32 v150, v104
	v_sub_f32_e32 v100, v100, v2
	v_add_f32_e32 v3, v146, v3
	v_exp_f32_e32 v151, v100
	v_sub_f32_e32 v100, v101, v2
	v_add_f32_e32 v3, v147, v3
	v_exp_f32_e32 v152, v100
	v_sub_f32_e32 v100, v102, v2
	v_add_f32_e32 v3, v148, v3
	v_exp_f32_e32 v153, v100
	v_sub_f32_e32 v100, v103, v2
	v_add_f32_e32 v3, v150, v3
	v_exp_f32_e32 v154, v100
	v_add_f32_e32 v3, v151, v3
	v_add_f32_e32 v3, v152, v3
	v_add_f32_e32 v3, v153, v3
	v_cmp_gt_f32_e32 vcc, v2, v126
	v_add_f32_e32 v155, v154, v3
	s_cbranch_vccz .LBB0_575
	v_sub_f32_e32 v3, v126, v2
	v_exp_f32_e32 v112, v3
	v_mov_b32_e32 v3, v127
	v_mov_b32_e32 v129, v125
	v_fma_f32 v128, v124, v112, v155
	v_pk_mul_f32 v[102:103], v[82:83], v[112:113] op_sel_hi:[1,0]
	v_pk_mul_f32 v[100:101], v[80:81], v[112:113] op_sel_hi:[1,0]
	v_pk_mul_f32 v[106:107], v[78:79], v[112:113] op_sel_hi:[1,0]
	v_pk_mul_f32 v[104:105], v[76:77], v[112:113] op_sel_hi:[1,0]
	v_pk_mul_f32 v[110:111], v[74:75], v[112:113] op_sel_hi:[1,0]
	v_pk_mul_f32 v[108:109], v[72:73], v[112:113] op_sel_hi:[1,0]
	v_pk_mul_f32 v[114:115], v[70:71], v[112:113] op_sel_hi:[1,0]
	v_pk_mul_f32 v[112:113], v[68:69], v[112:113] op_sel_hi:[1,0]
	s_cbranch_execnz .LBB0_559

.LBB0_559:
	v_add_u32_e32 v69, 0x83, v149
	v_sub_u32_e32 v70, 0xffffff7d, v149
	v_max_i32_e32 v69, v69, v70
	v_cmp_lt_u32_e32 vcc, s65, v69
	v_add_u32_e32 v70, 0x82, v149
	v_sub_u32_e32 v71, 0xffffff7e, v149
	v_mul_f32_e32 v68, 0x3e38aa3b, v96
	s_and_b64 vcc, s[8:9], vcc
	v_max_i32_e32 v70, v70, v71
	v_cndmask_b32_e32 v68, v68, v221, vcc
	v_cmp_lt_u32_e32 vcc, s65, v70
	v_add_u32_e32 v72, 0x81, v149
	v_sub_u32_e32 v73, 0xffffff7f, v149
	v_mul_f32_e32 v69, 0x3e38aa3b, v97
	s_and_b64 vcc, s[8:9], vcc
	v_max_i32_e32 v72, v72, v73
	v_cndmask_b32_e32 v69, v69, v221, vcc
	v_cmp_lt_u32_e32 vcc, s65, v72
	v_add_u32_e32 v73, 0x80, v149
	v_sub_u32_e32 v74, 0xffffff80, v149
	v_mul_f32_e32 v71, 0x3e38aa3b, v98
	s_and_b64 vcc, s[8:9], vcc
	v_max_i32_e32 v73, v73, v74
	v_cndmask_b32_e32 v71, v71, v221, vcc
	v_cmp_lt_u32_e32 vcc, s65, v73
	v_mul_f32_e32 v72, 0x3e38aa3b, v99
	s_and_b64 vcc, s[8:9], vcc
	v_max3_f32 v70, v68, s82, v69
	v_cndmask_b32_e32 v72, v72, v221, vcc
	v_mul_f32_e32 v73, 0x3e38aa3b, v92
	v_mul_f32_e32 v74, 0x3e38aa3b, v93
	v_max3_f32 v70, v70, v71, v72
	v_cndmask_b32_e64 v73, v73, v221, s[40:41]
	v_cndmask_b32_e64 v74, v74, v221, s[42:43]
	v_mul_f32_e32 v75, 0x3e38aa3b, v94
	v_mul_f32_e32 v76, 0x3e38aa3b, v95
	v_max3_f32 v70, v70, v73, v74
	v_cndmask_b32_e64 v75, v75, v221, s[44:45]
	v_cndmask_b32_e64 v76, v76, v221, s[46:47]
	v_mul_f32_e32 v77, 0x3e38aa3b, v88
	v_mul_f32_e32 v78, 0x3e38aa3b, v89
	v_max3_f32 v70, v70, v75, v76
	v_cndmask_b32_e64 v77, v77, v221, s[48:49]
	v_cndmask_b32_e64 v78, v78, v221, s[50:51]
	v_mul_f32_e32 v79, 0x3e38aa3b, v90
	v_mul_f32_e32 v80, 0x3e38aa3b, v91
	v_max3_f32 v70, v70, v77, v78
	v_cndmask_b32_e64 v79, v79, v221, s[52:53]
	v_cndmask_b32_e64 v80, v80, v221, s[54:55]
	v_mul_f32_e32 v81, 0x3e38aa3b, v84
	v_mul_f32_e32 v82, 0x3e38aa3b, v85
	v_max3_f32 v70, v70, v79, v80
	v_cndmask_b32_e64 v81, v81, v221, s[56:57]
	v_cndmask_b32_e64 v82, v82, v221, s[58:59]
	v_mul_f32_e32 v83, 0x3e38aa3b, v86
	v_mul_f32_e32 v84, 0x3e38aa3b, v87
	v_max3_f32 v70, v70, v81, v82
	v_cndmask_b32_e64 v83, v83, v221, s[60:61]
	v_cndmask_b32_e64 v99, v84, v221, s[62:63]
	v_max3_f32 v70, v70, v83, v99
	v_mov_b32_e32 v84, v70
	s_waitcnt lgkmcnt(0)
	s_nop 1
	v_permlane16_swap_b32_e32 v84, v70
	v_max_f32_e32 v70, v70, v84
	v_mov_b32_e32 v84, v70
	s_waitcnt lgkmcnt(0)
	s_nop 1
	v_permlane32_swap_b32_e32 v84, v70
	v_max3_f32 v127, v3, v70, v84
	v_sub_f32_e32 v68, v68, v127
	v_exp_f32_e32 v84, v68
	v_sub_f32_e32 v68, v69, v127
	v_exp_f32_e32 v85, v68
	v_sub_f32_e32 v68, v71, v127
	v_exp_f32_e32 v86, v68
	v_sub_f32_e32 v68, v72, v127
	v_exp_f32_e32 v87, v68
	v_sub_f32_e32 v69, v73, v127
	v_add_f32_e32 v68, 0, v84
	v_exp_f32_e32 v88, v69
	v_sub_f32_e32 v69, v74, v127
	v_add_f32_e32 v68, v85, v68
	v_exp_f32_e32 v90, v69
	v_sub_f32_e32 v69, v75, v127
	v_add_f32_e32 v68, v86, v68
	v_exp_f32_e32 v92, v69
	v_sub_f32_e32 v69, v76, v127
	v_add_f32_e32 v68, v87, v68
	v_exp_f32_e32 v94, v69
	v_sub_f32_e32 v69, v77, v127
	v_add_f32_e32 v68, v88, v68
	v_exp_f32_e32 v89, v69
	v_sub_f32_e32 v69, v78, v127
	v_add_f32_e32 v68, v90, v68
	v_exp_f32_e32 v91, v69
	v_sub_f32_e32 v69, v79, v127
	v_add_f32_e32 v68, v92, v68
	v_exp_f32_e32 v93, v69
	v_sub_f32_e32 v69, v80, v127
	v_add_f32_e32 v68, v94, v68
	v_exp_f32_e32 v95, v69
	v_sub_f32_e32 v69, v81, v127
	v_add_f32_e32 v68, v89, v68
	v_exp_f32_e32 v96, v69
	v_sub_f32_e32 v69, v82, v127
	v_add_f32_e32 v68, v91, v68
	v_exp_f32_e32 v97, v69
	v_sub_f32_e32 v69, v83, v127
	v_add_f32_e32 v68, v93, v68
	v_exp_f32_e32 v98, v69
	v_sub_f32_e32 v69, v99, v127
	v_add_f32_e32 v68, v95, v68
	v_exp_f32_e32 v99, v69
	v_add_f32_e32 v68, v96, v68
	v_add_f32_e32 v68, v97, v68
	v_add_f32_e32 v68, v98, v68
	v_cmp_gt_f32_e32 vcc, v127, v3
	v_add_f32_e32 v149, v99, v68
	s_cbranch_vccz .LBB0_576
	v_sub_f32_e32 v68, v3, v127
	v_exp_f32_e32 v80, v68
	v_mov_b32_e32 v126, v2
	v_mov_b32_e32 v124, v128
	v_fma_f32 v125, v129, v80, v149
	v_pk_mul_f32 v[70:71], v[62:63], v[80:81] op_sel_hi:[1,0]
	v_pk_mul_f32 v[68:69], v[60:61], v[80:81] op_sel_hi:[1,0]
	v_pk_mul_f32 v[74:75], v[58:59], v[80:81] op_sel_hi:[1,0]
	v_pk_mul_f32 v[72:73], v[56:57], v[80:81] op_sel_hi:[1,0]
	v_pk_mul_f32 v[78:79], v[54:55], v[80:81] op_sel_hi:[1,0]
	v_pk_mul_f32 v[76:77], v[52:53], v[80:81] op_sel_hi:[1,0]
	v_pk_mul_f32 v[82:83], v[66:67], v[80:81] op_sel_hi:[1,0]
	v_pk_mul_f32 v[80:81], v[64:65], v[80:81] op_sel_hi:[1,0]
	s_cbranch_execnz .LBB0_562

.LBB0_567:
	ds_read_b128 v[84:87], v123 offset:18432
	ds_read_b128 v[88:91], v123 offset:18496
	ds_read_b128 v[92:95], v123 offset:20736
	ds_read_b128 v[100:103], v123 offset:20800
	ds_read_b128 v[104:107], v123 offset:23040
	ds_read_b128 v[108:111], v123 offset:23104
	ds_read_b128 v[112:115], v123 offset:25344
	ds_read_b128 v[140:143], v123 offset:25408
	s_cmp_lt_i32 s40, s13
	s_cselect_b64 s[8:9], -1, 0
	s_and_b64 s[40:41], s[8:9], exec
	s_cselect_b32 s40, 0, s13
	s_cselect_b32 s41, s76, 0x1000
	s_waitcnt lgkmcnt(7)
	v_mfma_f32_16x16x32_bf16 v[96:99], v[84:87], v[12:15], 0
	s_lshl_b32 s40, s40, 6
	s_sub_i32 s40, s40, s41
	v_add_u32_e32 v150, s40, v133
	v_mfma_f32_16x16x32_bf16 v[84:87], v[84:87], v[20:23], 0
	v_add_u32_e32 v2, 51, v150
	v_sub_u32_e32 v3, 0xffffffcd, v150
	v_max_i32_e32 v2, v2, v3
	s_waitcnt lgkmcnt(6)
	v_mfma_f32_16x16x32_bf16 v[144:147], v[88:91], v[16:19], v[96:99]
	v_add_u32_e32 v3, 50, v150
	v_cmp_lt_u32_e32 vcc, s65, v2
	s_and_b64 s[40:41], s[8:9], vcc
	v_mfma_f32_16x16x32_bf16 v[96:99], v[88:91], v[24:27], v[84:87]
	s_waitcnt lgkmcnt(5)
	v_mfma_f32_16x16x32_bf16 v[84:87], v[92:95], v[12:15], 0
	s_nop 1
	v_mul_f32_e32 v0, 0x3e38aa3b, v144
	v_mul_f32_e32 v2, 0x3e38aa3b, v145
	v_cndmask_b32_e64 v0, v0, v221, s[40:41]
	v_mfma_f32_16x16x32_bf16 v[88:91], v[92:95], v[20:23], 0
	s_waitcnt lgkmcnt(4)
	v_mfma_f32_16x16x32_bf16 v[152:155], v[100:103], v[16:19], v[84:87]
	s_waitcnt lgkmcnt(3)
	v_mfma_f32_16x16x32_bf16 v[84:87], v[104:107], v[12:15], 0
	v_mfma_f32_16x16x32_bf16 v[92:95], v[100:103], v[24:27], v[88:91]
	v_mfma_f32_16x16x32_bf16 v[88:91], v[104:107], v[20:23], 0
	s_waitcnt lgkmcnt(2)
	v_mfma_f32_16x16x32_bf16 v[100:103], v[108:111], v[16:19], v[84:87]
	s_waitcnt lgkmcnt(1)
	v_mfma_f32_16x16x32_bf16 v[84:87], v[112:115], v[12:15], 0
	v_mfma_f32_16x16x32_bf16 v[104:107], v[112:115], v[20:23], 0
	v_sub_u32_e32 v112, 0xffffffdd, v150
	v_sub_u32_e32 v113, 0xffffffde, v150
	v_sub_u32_e32 v114, 0xffffffdf, v150
	v_mfma_f32_16x16x32_bf16 v[88:91], v[108:111], v[24:27], v[88:91]
	v_sub_u32_e32 v115, 0xffffffe0, v150
	v_mul_f32_e32 v100, 0x3e38aa3b, v100
	v_mul_f32_e32 v101, 0x3e38aa3b, v101
	s_waitcnt lgkmcnt(0)
	v_mfma_f32_16x16x32_bf16 v[108:111], v[140:143], v[16:19], v[84:87]
	v_mul_f32_e32 v102, 0x3e38aa3b, v102
	v_mul_f32_e32 v103, 0x3e38aa3b, v103
	v_mfma_f32_16x16x32_bf16 v[84:87], v[140:143], v[24:27], v[104:107]
	s_nop 2
	v_sub_u32_e32 v104, 0xffffffce, v150
	v_max_i32_e32 v3, v3, v104
	v_add_u32_e32 v105, 49, v150
	v_sub_u32_e32 v106, 0xffffffcf, v150
	v_cmp_lt_u32_e32 vcc, s65, v3
	v_max_i32_e32 v105, v105, v106
	v_add_u32_e32 v106, 48, v150
	v_sub_u32_e32 v107, 0xffffffd0, v150
	s_and_b64 s[42:43], s[8:9], vcc
	v_cmp_lt_u32_e32 vcc, s65, v105
	v_max_i32_e32 v106, v106, v107
	v_add_u32_e32 v107, 35, v150
	s_and_b64 s[44:45], s[8:9], vcc
	v_cmp_lt_u32_e32 vcc, s65, v106
	v_max_i32_e32 v107, v107, v112
	v_add_u32_e32 v112, 34, v150
	s_and_b64 s[46:47], s[8:9], vcc
	v_cmp_lt_u32_e32 vcc, s65, v107
	v_max_i32_e32 v112, v112, v113
	v_add_u32_e32 v113, 33, v150
	s_and_b64 s[48:49], s[8:9], vcc
	v_cmp_lt_u32_e32 vcc, s65, v112
	v_max_i32_e32 v113, v113, v114
	v_add_u32_e32 v114, 32, v150
	s_and_b64 s[50:51], s[8:9], vcc
	v_cmp_lt_u32_e32 vcc, s65, v113
	v_max_i32_e32 v114, v114, v115
	s_and_b64 s[52:53], s[8:9], vcc
	v_cmp_lt_u32_e32 vcc, s65, v114
	v_add_u32_e32 v114, 19, v150
	v_sub_u32_e32 v115, 0xffffffed, v150
	v_max_i32_e32 v114, v114, v115
	s_and_b64 s[54:55], s[8:9], vcc
	v_cmp_lt_u32_e32 vcc, s65, v114
	v_add_u32_e32 v114, 18, v150
	v_sub_u32_e32 v115, 0xffffffee, v150
	v_max_i32_e32 v114, v114, v115
	s_and_b64 s[56:57], s[8:9], vcc
	v_cmp_lt_u32_e32 vcc, s65, v114
	v_add_u32_e32 v114, 17, v150
	v_sub_u32_e32 v115, 0xffffffef, v150
	v_max_i32_e32 v114, v114, v115
	s_and_b64 s[58:59], s[8:9], vcc
	v_cmp_lt_u32_e32 vcc, s65, v114
	v_add_u32_e32 v114, 16, v150
	v_sub_u32_e32 v115, -16, v150
	v_max_i32_e32 v114, v114, v115
	s_and_b64 s[60:61], s[8:9], vcc
	v_cmp_lt_u32_e32 vcc, s65, v114
	v_add_u32_e32 v114, 3, v150
	v_sub_u32_e32 v115, -3, v150
	v_max_i32_e32 v114, v114, v115
	s_and_b64 s[62:63], s[8:9], vcc
	v_cmp_lt_u32_e32 vcc, s65, v114
	v_add_u32_e32 v114, 2, v150
	v_sub_u32_e32 v115, -2, v150
	v_cndmask_b32_e64 v3, v2, v221, s[42:43]
	v_mul_f32_e32 v104, 0x3e38aa3b, v146
	v_mul_f32_e32 v105, 0x3e38aa3b, v147
	v_mul_f32_e32 v108, 0x3e38aa3b, v108
	s_and_b64 vcc, s[8:9], vcc
	v_max_i32_e32 v114, v114, v115
	v_max3_f32 v2, v0, s82, v3
	v_cndmask_b32_e64 v104, v104, v221, s[44:45]
	v_cndmask_b32_e64 v105, v105, v221, s[46:47]
	v_mul_f32_e32 v106, 0x3e38aa3b, v152
	v_mul_f32_e32 v107, 0x3e38aa3b, v153
	v_cndmask_b32_e32 v108, v108, v221, vcc
	v_cmp_lt_u32_e32 vcc, s65, v114
	v_add_u32_e32 v114, 1, v150
	v_not_b32_e32 v115, v150
	v_max3_f32 v2, v2, v104, v105
	v_cndmask_b32_e64 v106, v106, v221, s[48:49]
	v_cndmask_b32_e64 v107, v107, v221, s[50:51]
	v_mul_f32_e32 v112, 0x3e38aa3b, v154
	v_mul_f32_e32 v113, 0x3e38aa3b, v155
	v_mul_f32_e32 v109, 0x3e38aa3b, v109
	s_and_b64 vcc, s[8:9], vcc
	v_max_i32_e32 v114, v114, v115
	v_max3_f32 v2, v2, v106, v107
	v_cndmask_b32_e64 v112, v112, v221, s[52:53]
	v_cndmask_b32_e64 v113, v113, v221, s[54:55]
	v_cndmask_b32_e32 v109, v109, v221, vcc
	v_cmp_lt_u32_e32 vcc, s65, v114
	v_sub_u32_e32 v114, 0, v150
	v_max3_f32 v2, v2, v112, v113
	v_cndmask_b32_e64 v100, v100, v221, s[56:57]
	v_cndmask_b32_e64 v101, v101, v221, s[58:59]
	v_mul_f32_e32 v110, 0x3e38aa3b, v110
	s_and_b64 vcc, s[8:9], vcc
	v_max_i32_e32 v114, v150, v114
	v_max3_f32 v2, v2, v100, v101
	v_cndmask_b32_e64 v102, v102, v221, s[60:61]
	v_cndmask_b32_e64 v103, v103, v221, s[62:63]
	v_cndmask_b32_e32 v110, v110, v221, vcc
	v_cmp_lt_u32_e32 vcc, s65, v114
	v_max3_f32 v2, v2, v102, v103
	v_mul_f32_e32 v111, 0x3e38aa3b, v111
	s_and_b64 vcc, s[8:9], vcc
	v_max3_f32 v2, v2, v108, v109
	v_cndmask_b32_e32 v111, v111, v221, vcc
	v_max3_f32 v2, v2, v110, v111
	v_mov_b32_e32 v114, v2
	s_waitcnt lgkmcnt(0)
	s_nop 1
	v_permlane16_swap_b32_e32 v114, v2
	v_max_f32_e32 v2, v2, v114
	v_mov_b32_e32 v114, v2
	s_waitcnt lgkmcnt(0)
	s_nop 1
	v_permlane32_swap_b32_e32 v114, v2
	v_max3_f32 v2, v126, v2, v114
	v_sub_f32_e32 v0, v0, v2
	v_exp_f32_e32 v0, v0
	v_sub_f32_e32 v3, v3, v2
	v_exp_f32_e32 v139, v3
	v_sub_f32_e32 v104, v104, v2
	v_exp_f32_e32 v140, v104
	v_sub_f32_e32 v104, v105, v2
	v_exp_f32_e32 v141, v104
	v_sub_f32_e32 v104, v106, v2
	v_add_f32_e32 v114, 0, v0
	v_exp_f32_e32 v142, v104
	v_sub_f32_e32 v104, v107, v2
	v_add_f32_e32 v3, v139, v114
	v_exp_f32_e32 v143, v104
	v_sub_f32_e32 v104, v112, v2
	v_add_f32_e32 v3, v140, v3
	v_exp_f32_e32 v144, v104
	v_sub_f32_e32 v104, v113, v2
	v_add_f32_e32 v3, v141, v3
	v_exp_f32_e32 v145, v104
	v_sub_f32_e32 v100, v100, v2
	v_add_f32_e32 v3, v142, v3
	v_exp_f32_e32 v146, v100
	v_sub_f32_e32 v100, v101, v2
	v_add_f32_e32 v3, v143, v3
	v_exp_f32_e32 v147, v100
	v_sub_f32_e32 v100, v102, v2
	v_add_f32_e32 v3, v144, v3
	v_exp_f32_e32 v148, v100
	v_sub_f32_e32 v100, v103, v2
	v_add_f32_e32 v3, v145, v3
	v_exp_f32_e32 v149, v100
	v_sub_f32_e32 v100, v108, v2
	v_add_f32_e32 v3, v146, v3
	v_exp_f32_e32 v151, v100
	v_sub_f32_e32 v100, v109, v2
	v_add_f32_e32 v3, v147, v3
	v_exp_f32_e32 v152, v100
	v_sub_f32_e32 v100, v110, v2
	v_add_f32_e32 v3, v148, v3
	v_exp_f32_e32 v153, v100
	v_sub_f32_e32 v100, v111, v2
	v_add_f32_e32 v3, v149, v3
	v_exp_f32_e32 v154, v100
	v_add_f32_e32 v3, v151, v3
	v_add_f32_e32 v3, v152, v3
	v_add_f32_e32 v3, v153, v3
	v_cmp_gt_f32_e32 vcc, v2, v126
	v_add_f32_e32 v155, v154, v3
	s_cbranch_vccz .LBB0_577
	v_sub_f32_e32 v3, v126, v2
	v_exp_f32_e32 v112, v3
	v_mov_b32_e32 v3, v127
	v_mov_b32_e32 v129, v125
	v_fma_f32 v128, v124, v112, v155
	v_pk_mul_f32 v[102:103], v[82:83], v[112:113] op_sel_hi:[1,0]
	v_pk_mul_f32 v[100:101], v[80:81], v[112:113] op_sel_hi:[1,0]
	v_pk_mul_f32 v[106:107], v[78:79], v[112:113] op_sel_hi:[1,0]
	v_pk_mul_f32 v[104:105], v[76:77], v[112:113] op_sel_hi:[1,0]
	v_pk_mul_f32 v[110:111], v[74:75], v[112:113] op_sel_hi:[1,0]
	v_pk_mul_f32 v[108:109], v[72:73], v[112:113] op_sel_hi:[1,0]
	v_pk_mul_f32 v[114:115], v[70:71], v[112:113] op_sel_hi:[1,0]
	v_pk_mul_f32 v[112:113], v[68:69], v[112:113] op_sel_hi:[1,0]
	s_cbranch_execnz .LBB0_570

.LBB0_570:
	v_add_u32_e32 v69, 0x43, v150
	v_sub_u32_e32 v70, 0xffffffbd, v150
	v_max_i32_e32 v69, v69, v70
	v_cmp_lt_u32_e32 vcc, s65, v69
	v_add_u32_e32 v70, 0x42, v150
	v_sub_u32_e32 v71, 0xffffffbe, v150
	v_mul_f32_e32 v68, 0x3e38aa3b, v96
	s_and_b64 vcc, s[8:9], vcc
	v_max_i32_e32 v70, v70, v71
	v_cndmask_b32_e32 v68, v68, v221, vcc
	v_cmp_lt_u32_e32 vcc, s65, v70
	v_add_u32_e32 v72, 0x41, v150
	v_sub_u32_e32 v73, 0xffffffbf, v150
	v_mul_f32_e32 v69, 0x3e38aa3b, v97
	s_and_b64 vcc, s[8:9], vcc
	v_max_i32_e32 v72, v72, v73
	v_cndmask_b32_e32 v69, v69, v221, vcc
	v_cmp_lt_u32_e32 vcc, s65, v72
	v_add_u32_e32 v73, 64, v150
	v_sub_u32_e32 v74, 0xffffffc0, v150
	v_mul_f32_e32 v71, 0x3e38aa3b, v98
	s_and_b64 vcc, s[8:9], vcc
	v_max_i32_e32 v73, v73, v74
	v_cndmask_b32_e32 v71, v71, v221, vcc
	v_cmp_lt_u32_e32 vcc, s65, v73
	v_mul_f32_e32 v72, 0x3e38aa3b, v99
	s_and_b64 vcc, s[8:9], vcc
	v_max3_f32 v70, v68, s82, v69
	v_cndmask_b32_e32 v72, v72, v221, vcc
	v_mul_f32_e32 v73, 0x3e38aa3b, v92
	v_mul_f32_e32 v74, 0x3e38aa3b, v93
	v_max3_f32 v70, v70, v71, v72
	v_cndmask_b32_e64 v73, v73, v221, s[40:41]
	v_cndmask_b32_e64 v74, v74, v221, s[42:43]
	v_mul_f32_e32 v75, 0x3e38aa3b, v94
	v_mul_f32_e32 v76, 0x3e38aa3b, v95
	v_max3_f32 v70, v70, v73, v74
	v_cndmask_b32_e64 v75, v75, v221, s[44:45]
	v_cndmask_b32_e64 v76, v76, v221, s[46:47]
	v_mul_f32_e32 v77, 0x3e38aa3b, v88
	v_mul_f32_e32 v78, 0x3e38aa3b, v89
	v_max3_f32 v70, v70, v75, v76
	v_cndmask_b32_e64 v77, v77, v221, s[48:49]
	v_cndmask_b32_e64 v78, v78, v221, s[50:51]
	v_mul_f32_e32 v79, 0x3e38aa3b, v90
	v_mul_f32_e32 v80, 0x3e38aa3b, v91
	v_max3_f32 v70, v70, v77, v78
	v_cndmask_b32_e64 v79, v79, v221, s[52:53]
	v_cndmask_b32_e64 v80, v80, v221, s[54:55]
	v_mul_f32_e32 v81, 0x3e38aa3b, v84
	v_mul_f32_e32 v82, 0x3e38aa3b, v85
	v_max3_f32 v70, v70, v79, v80
	v_cndmask_b32_e64 v81, v81, v221, s[56:57]
	v_cndmask_b32_e64 v82, v82, v221, s[58:59]
	v_mul_f32_e32 v83, 0x3e38aa3b, v86
	v_mul_f32_e32 v84, 0x3e38aa3b, v87
	v_max3_f32 v70, v70, v81, v82
	v_cndmask_b32_e64 v83, v83, v221, s[60:61]
	v_cndmask_b32_e64 v99, v84, v221, s[62:63]
	v_max3_f32 v70, v70, v83, v99
	v_mov_b32_e32 v84, v70
	s_waitcnt lgkmcnt(0)
	s_nop 1
	v_permlane16_swap_b32_e32 v84, v70
	v_max_f32_e32 v70, v70, v84
	v_mov_b32_e32 v84, v70
	s_waitcnt lgkmcnt(0)
	s_nop 1
	v_permlane32_swap_b32_e32 v84, v70
	v_max3_f32 v127, v3, v70, v84
	v_sub_f32_e32 v68, v68, v127
	v_exp_f32_e32 v84, v68
	v_sub_f32_e32 v68, v69, v127
	v_exp_f32_e32 v85, v68
	v_sub_f32_e32 v68, v71, v127
	v_exp_f32_e32 v86, v68
	v_sub_f32_e32 v68, v72, v127
	v_exp_f32_e32 v87, v68
	v_sub_f32_e32 v69, v73, v127
	v_add_f32_e32 v68, 0, v84
	v_exp_f32_e32 v88, v69
	v_sub_f32_e32 v69, v74, v127
	v_add_f32_e32 v68, v85, v68
	v_exp_f32_e32 v90, v69
	v_sub_f32_e32 v69, v75, v127
	v_add_f32_e32 v68, v86, v68
	v_exp_f32_e32 v92, v69
	v_sub_f32_e32 v69, v76, v127
	v_add_f32_e32 v68, v87, v68
	v_exp_f32_e32 v94, v69
	v_sub_f32_e32 v69, v77, v127
	v_add_f32_e32 v68, v88, v68
	v_exp_f32_e32 v89, v69
	v_sub_f32_e32 v69, v78, v127
	v_add_f32_e32 v68, v90, v68
	v_exp_f32_e32 v91, v69
	v_sub_f32_e32 v69, v79, v127
	v_add_f32_e32 v68, v92, v68
	v_exp_f32_e32 v93, v69
	v_sub_f32_e32 v69, v80, v127
	v_add_f32_e32 v68, v94, v68
	v_exp_f32_e32 v95, v69
	v_sub_f32_e32 v69, v81, v127
	v_add_f32_e32 v68, v89, v68
	v_exp_f32_e32 v96, v69
	v_sub_f32_e32 v69, v82, v127
	v_add_f32_e32 v68, v91, v68
	v_exp_f32_e32 v97, v69
	v_sub_f32_e32 v69, v83, v127
	v_add_f32_e32 v68, v93, v68
	v_exp_f32_e32 v98, v69
	v_sub_f32_e32 v69, v99, v127
	v_add_f32_e32 v68, v95, v68
	v_exp_f32_e32 v99, v69
	v_add_f32_e32 v68, v96, v68
	v_add_f32_e32 v68, v97, v68
	v_add_f32_e32 v68, v98, v68
	v_cmp_gt_f32_e32 vcc, v127, v3
	v_add_f32_e32 v137, v99, v68
	s_cbranch_vccz .LBB0_578
	v_sub_f32_e32 v68, v3, v127
	v_exp_f32_e32 v80, v68
	v_mov_b32_e32 v126, v2
	v_mov_b32_e32 v124, v128
	v_fma_f32 v125, v129, v80, v137
	v_pk_mul_f32 v[70:71], v[62:63], v[80:81] op_sel_hi:[1,0]
	v_pk_mul_f32 v[68:69], v[60:61], v[80:81] op_sel_hi:[1,0]
	v_pk_mul_f32 v[74:75], v[58:59], v[80:81] op_sel_hi:[1,0]
	v_pk_mul_f32 v[72:73], v[56:57], v[80:81] op_sel_hi:[1,0]
	v_pk_mul_f32 v[78:79], v[54:55], v[80:81] op_sel_hi:[1,0]
	v_pk_mul_f32 v[76:77], v[52:53], v[80:81] op_sel_hi:[1,0]
	v_pk_mul_f32 v[82:83], v[66:67], v[80:81] op_sel_hi:[1,0]
	v_pk_mul_f32 v[80:81], v[64:65], v[80:81] op_sel_hi:[1,0]
	s_cbranch_execnz .LBB0_573

.LBB0_1372:
	s_andn2_b64 vcc, exec, s[0:1]
	s_cbranch_vccnz .LBB0_1555
	s_getreg_b32 s80, hwreg(HW_REG_XCC_ID, 0, 4)
	s_and_b32 s0, s22, 16
	v_readlane_b32 s2, v252, 4
	v_readlane_b32 s3, v252, 5
	s_add_u32 s0, s0, 36
	s_lshl_b32 s0, s0, 2
	s_and_b32 s80, s80, 7
	s_mov_b32 s81, 0
	v_readlane_b32 s77, v254, 55
	s_nop 0
	s_bfe_u32 s9, s77, 0x50003
	s_and_b32 s8, s77, 7
	s_lshl_b32 s8, s8, 2
	s_lshr_b32 s10, s9, 1
	s_and_b32 s10, s10, 3
	s_add_u32 s8, s8, s10
	s_and_b32 s10, s9, 0x19
	s_lshr_b32 s77, s77, 8
	s_or_b32 s10, s10, s77
	s_cmp_eq_u32 s10, 0
	s_cselect_b32 s77, s8, -1
	s_add_u32 s6, s2, s0
	s_addc_u32 s7, s3, 0
	v_mov_b32_e32 v0, v179
	s_waitcnt vmcnt(63) expcnt(7) lgkmcnt(15)
	s_barrier
	s_branch .LBB0_1376

.LBB0_1388:
	ds_read_b128 v[116:119], v155
	ds_read_b128 v[120:123], v155 offset:64
	ds_read_b128 v[124:127], v155 offset:128
	ds_read_b128 v[128:131], v155 offset:192
	ds_read_b128 v[132:135], v155 offset:4352
	ds_read_b128 v[136:139], v155 offset:4416
	ds_read_b128 v[140:143], v155 offset:4480
	ds_read_b128 v[144:147], v155 offset:4544
	ds_read_b128 v[172:175], v155 offset:8704
	ds_read_b128 v[180:183], v155 offset:8768
	ds_read_b128 v[184:187], v155 offset:8832
	ds_read_b128 v[188:191], v155 offset:8896
	ds_read_b128 v[192:195], v155 offset:13056
	ds_read_b128 v[196:199], v155 offset:13120
	ds_read_b128 v[200:203], v155 offset:13184
	ds_read_b128 v[204:207], v155 offset:13248
	s_waitcnt lgkmcnt(14)
	v_mfma_f32_16x16x32_bf16 v[216:219], v[116:119], v[4:7], 0
	v_and_b32_e32 v2, 64, v215
	v_xor_b32_e32 v0, 16, v215
	v_add_u32_e32 v2, 64, v2
	v_mfma_f32_16x16x32_bf16 v[116:119], v[116:119], v[20:23], 0
	v_cmp_lt_i32_e32 vcc, v0, v2
	v_mfma_f32_16x16x32_bf16 v[216:219], v[120:123], v[8:11], v[216:219]
	s_nop 0
	v_cndmask_b32_e32 v0, v215, v0, vcc
	v_lshlrev_b32_e32 v169, 2, v0
	v_xor_b32_e32 v0, 32, v215
	v_mfma_f32_16x16x32_bf16 v[116:119], v[120:123], v[24:27], v[116:119]
	v_cmp_lt_i32_e32 vcc, v0, v2
	s_waitcnt lgkmcnt(13)
	v_mfma_f32_16x16x32_bf16 v[120:123], v[124:127], v[12:15], v[216:219]
	v_cndmask_b32_e32 v0, v215, v0, vcc
	v_lshlrev_b32_e32 v168, 2, v0
	v_mfma_f32_16x16x32_bf16 v[116:119], v[124:127], v[28:31], v[116:119]
	s_waitcnt lgkmcnt(12)
	v_mfma_f32_16x16x32_bf16 v[216:219], v[128:131], v[16:19], v[120:123]
	v_mfma_f32_16x16x32_bf16 v[120:123], v[128:131], v[32:35], v[116:119]
	s_waitcnt lgkmcnt(11)
	v_mfma_f32_16x16x32_bf16 v[116:119], v[132:135], v[4:7], 0
	s_nop 4
	v_mul_f32_e32 v0, 0x3e0293ee, v216
	v_mul_f32_e32 v2, 0x3e0293ee, v217
	v_max3_f32 v0, v0, s82, v2
	v_mfma_f32_16x16x32_bf16 v[124:127], v[132:135], v[20:23], 0
	v_mul_f32_e32 v2, 0x3e0293ee, v218
	v_mul_f32_e32 v3, 0x3e0293ee, v219
	v_max3_f32 v0, v0, v2, v3
	s_waitcnt lgkmcnt(10)
	v_mfma_f32_16x16x32_bf16 v[116:119], v[136:139], v[8:11], v[116:119]
	v_mfma_f32_16x16x32_bf16 v[124:127], v[136:139], v[24:27], v[124:127]
	s_waitcnt lgkmcnt(9)
	v_mfma_f32_16x16x32_bf16 v[116:119], v[140:143], v[12:15], v[116:119]
	v_mfma_f32_16x16x32_bf16 v[124:127], v[140:143], v[28:31], v[124:127]
	s_waitcnt lgkmcnt(8)
	v_mfma_f32_16x16x32_bf16 v[140:143], v[144:147], v[16:19], v[116:119]
	s_waitcnt lgkmcnt(7)
	v_mfma_f32_16x16x32_bf16 v[116:119], v[172:175], v[4:7], 0
	s_waitcnt lgkmcnt(6)
	v_mfma_f32_16x16x32_bf16 v[116:119], v[180:183], v[8:11], v[116:119]
	s_nop 3
	v_mul_f32_e32 v2, 0x3e0293ee, v140
	v_mul_f32_e32 v3, 0x3e0293ee, v141
	v_max3_f32 v0, v0, v2, v3
	s_waitcnt lgkmcnt(5)
	v_mfma_f32_16x16x32_bf16 v[116:119], v[184:187], v[12:15], v[116:119]
	v_mul_f32_e32 v2, 0x3e0293ee, v142
	v_mul_f32_e32 v3, 0x3e0293ee, v143
	v_max3_f32 v0, v0, v2, v3
	s_waitcnt lgkmcnt(4)
	v_mfma_f32_16x16x32_bf16 v[136:139], v[188:191], v[16:19], v[116:119]
	s_waitcnt lgkmcnt(3)
	v_mfma_f32_16x16x32_bf16 v[116:119], v[192:195], v[4:7], 0
	v_mfma_f32_16x16x32_bf16 v[132:135], v[192:195], v[20:23], 0
	s_nop 4
	v_mul_f32_e32 v2, 0x3e0293ee, v136
	v_mul_f32_e32 v3, 0x3e0293ee, v137
	v_max3_f32 v0, v0, v2, v3
	s_waitcnt lgkmcnt(2)
	v_mfma_f32_16x16x32_bf16 v[116:119], v[196:199], v[8:11], v[116:119]
	v_mul_f32_e32 v2, 0x3e0293ee, v138
	v_mul_f32_e32 v3, 0x3e0293ee, v139
	v_max3_f32 v0, v0, v2, v3
	v_mfma_f32_16x16x32_bf16 v[132:135], v[196:199], v[24:27], v[132:135]
	s_waitcnt lgkmcnt(1)
	v_mfma_f32_16x16x32_bf16 v[116:119], v[200:203], v[12:15], v[116:119]
	v_mfma_f32_16x16x32_bf16 v[128:131], v[144:147], v[32:35], v[124:127]
	v_mfma_f32_16x16x32_bf16 v[144:147], v[200:203], v[28:31], v[132:135]
	s_waitcnt lgkmcnt(0)
	v_mfma_f32_16x16x32_bf16 v[132:135], v[204:207], v[16:19], v[116:119]
	v_mfma_f32_16x16x32_bf16 v[124:127], v[172:175], v[20:23], 0
	v_mfma_f32_16x16x32_bf16 v[124:127], v[180:183], v[24:27], v[124:127]
	s_nop 5
	v_mul_f32_e32 v2, 0x3e0293ee, v132
	v_mul_f32_e32 v3, 0x3e0293ee, v133
	v_max3_f32 v0, v0, v2, v3
	v_mul_f32_e32 v2, 0x3e0293ee, v134
	v_mul_f32_e32 v3, 0x3e0293ee, v135
	v_max3_f32 v0, v0, v2, v3
	v_mov_b32_e32 v2, v0
	v_mfma_f32_16x16x32_bf16 v[124:127], v[184:187], v[28:31], v[124:127]
	s_waitcnt lgkmcnt(0)
	s_nop 1
	v_permlane16_swap_b32_e32 v2, v0
	v_max_f32_e32 v0, v0, v2
	v_mov_b32_e32 v2, v0
	v_mfma_f32_16x16x32_bf16 v[124:127], v[188:191], v[32:35], v[124:127]
	s_waitcnt lgkmcnt(0)
	s_nop 1
	v_permlane32_swap_b32_e32 v2, v0
	v_max3_f32 v172, v170, v0, v2
	v_fma_f32 v0, v216, s74, -v172
	v_exp_f32_e32 v0, v0
	v_fma_f32 v3, v217, s74, -v172
	v_exp_f32_e32 v174, v3
	v_fma_f32 v3, v218, s74, -v172
	v_exp_f32_e32 v175, v3
	v_fma_f32 v3, v219, s74, -v172
	v_exp_f32_e32 v176, v3
	v_fma_f32 v3, v140, s74, -v172
	v_add_f32_e32 v2, 0, v0
	v_exp_f32_e32 v177, v3
	v_fma_f32 v3, v141, s74, -v172
	v_add_f32_e32 v2, v174, v2
	v_exp_f32_e32 v180, v3
	v_fma_f32 v3, v142, s74, -v172
	v_add_f32_e32 v2, v175, v2
	v_exp_f32_e32 v181, v3
	v_fma_f32 v3, v143, s74, -v172
	v_add_f32_e32 v2, v176, v2
	v_exp_f32_e32 v183, v3
	v_fma_f32 v3, v136, s74, -v172
	v_add_f32_e32 v2, v177, v2
	v_exp_f32_e32 v182, v3
	v_fma_f32 v3, v137, s74, -v172
	v_add_f32_e32 v2, v180, v2
	v_exp_f32_e32 v184, v3
	v_fma_f32 v3, v138, s74, -v172
	v_add_f32_e32 v2, v181, v2
	v_exp_f32_e32 v185, v3
	v_fma_f32 v3, v139, s74, -v172
	v_add_f32_e32 v2, v183, v2
	v_exp_f32_e32 v186, v3
	v_fma_f32 v3, v132, s74, -v172
	v_add_f32_e32 v2, v182, v2
	v_exp_f32_e32 v187, v3
	v_fma_f32 v3, v133, s74, -v172
	v_add_f32_e32 v2, v184, v2
	v_exp_f32_e32 v188, v3
	v_fma_f32 v3, v134, s74, -v172
	v_add_f32_e32 v2, v185, v2
	v_exp_f32_e32 v189, v3
	v_fma_f32 v3, v135, s74, -v172
	v_add_f32_e32 v2, v186, v2
	v_exp_f32_e32 v190, v3
	v_mfma_f32_16x16x32_bf16 v[116:119], v[204:207], v[32:35], v[144:147]
	v_add_f32_e32 v2, v187, v2
	v_add_f32_e32 v2, v188, v2
	v_add_f32_e32 v2, v189, v2
	v_cmp_gt_f32_e32 vcc, v172, v170
	v_add_f32_e32 v2, v190, v2
	s_cbranch_vccz .LBB0_1404
	v_sub_f32_e32 v3, v170, v172
	v_exp_f32_e32 v144, v3
	v_mov_b32_e32 v159, v157
	v_fma_f32 v158, v156, v144, v2
	v_pk_mul_f32 v[134:135], v[114:115], v[144:145] op_sel_hi:[1,0]
	v_pk_mul_f32 v[132:133], v[112:113], v[144:145] op_sel_hi:[1,0]
	v_pk_mul_f32 v[138:139], v[110:111], v[144:145] op_sel_hi:[1,0]
	v_pk_mul_f32 v[136:137], v[108:109], v[144:145] op_sel_hi:[1,0]
	v_pk_mul_f32 v[142:143], v[106:107], v[144:145] op_sel_hi:[1,0]
	v_pk_mul_f32 v[140:141], v[104:105], v[144:145] op_sel_hi:[1,0]
	v_pk_mul_f32 v[146:147], v[102:103], v[144:145] op_sel_hi:[1,0]
	v_pk_mul_f32 v[144:145], v[100:101], v[144:145] op_sel_hi:[1,0]
	s_cbranch_execnz .LBB0_1391

.LBB0_1391:
	v_mul_f32_e32 v2, 0x3e0293ee, v120
	v_mul_f32_e32 v3, 0x3e0293ee, v121
	v_max3_f32 v2, v2, s82, v3
	v_mul_f32_e32 v3, 0x3e0293ee, v122
	v_mul_f32_e32 v100, 0x3e0293ee, v123
	v_max3_f32 v2, v2, v3, v100
	v_mul_f32_e32 v3, 0x3e0293ee, v128
	v_mul_f32_e32 v100, 0x3e0293ee, v129
	v_max3_f32 v2, v2, v3, v100
	v_mul_f32_e32 v3, 0x3e0293ee, v130
	v_mul_f32_e32 v100, 0x3e0293ee, v131
	v_max3_f32 v2, v2, v3, v100
	v_mul_f32_e32 v3, 0x3e0293ee, v124
	v_mul_f32_e32 v100, 0x3e0293ee, v125
	v_max3_f32 v2, v2, v3, v100
	v_mul_f32_e32 v3, 0x3e0293ee, v126
	v_mul_f32_e32 v100, 0x3e0293ee, v127
	v_max3_f32 v2, v2, v3, v100
	v_mul_f32_e32 v3, 0x3e0293ee, v116
	v_mul_f32_e32 v100, 0x3e0293ee, v117
	v_max3_f32 v2, v2, v3, v100
	v_mul_f32_e32 v3, 0x3e0293ee, v118
	v_mul_f32_e32 v100, 0x3e0293ee, v119
	v_max3_f32 v2, v2, v3, v100
	v_mov_b32_e32 v3, v2
	s_waitcnt lgkmcnt(0)
	s_nop 1
	v_permlane16_swap_b32_e32 v3, v2
	v_max_f32_e32 v2, v2, v3
	v_mov_b32_e32 v3, v2
	s_waitcnt lgkmcnt(0)
	s_nop 1
	v_permlane32_swap_b32_e32 v3, v2
	v_max3_f32 v173, v171, v2, v3
	v_fma_f32 v2, v120, s74, -v173
	v_exp_f32_e32 v120, v2
	v_fma_f32 v2, v121, s74, -v173
	v_exp_f32_e32 v121, v2
	v_fma_f32 v2, v122, s74, -v173
	v_exp_f32_e32 v122, v2
	v_fma_f32 v2, v123, s74, -v173
	v_exp_f32_e32 v123, v2
	v_fma_f32 v3, v128, s74, -v173
	v_add_f32_e32 v2, 0, v120
	v_exp_f32_e32 v128, v3
	v_fma_f32 v3, v129, s74, -v173
	v_add_f32_e32 v2, v121, v2
	v_exp_f32_e32 v129, v3
	v_fma_f32 v3, v130, s74, -v173
	v_add_f32_e32 v2, v122, v2
	v_exp_f32_e32 v130, v3
	v_fma_f32 v3, v131, s74, -v173
	v_add_f32_e32 v2, v123, v2
	v_exp_f32_e32 v131, v3
	v_fma_f32 v3, v124, s74, -v173
	v_add_f32_e32 v2, v128, v2
	v_exp_f32_e32 v124, v3
	v_fma_f32 v3, v125, s74, -v173
	v_add_f32_e32 v2, v129, v2
	v_exp_f32_e32 v125, v3
	v_fma_f32 v3, v126, s74, -v173
	v_add_f32_e32 v2, v130, v2
	v_exp_f32_e32 v126, v3
	v_fma_f32 v3, v127, s74, -v173
	v_add_f32_e32 v2, v131, v2
	v_exp_f32_e32 v127, v3
	v_fma_f32 v3, v116, s74, -v173
	v_add_f32_e32 v2, v124, v2
	v_exp_f32_e32 v116, v3
	v_fma_f32 v3, v117, s74, -v173
	v_add_f32_e32 v2, v125, v2
	v_exp_f32_e32 v117, v3
	v_fma_f32 v3, v118, s74, -v173
	v_add_f32_e32 v2, v126, v2
	v_exp_f32_e32 v118, v3
	v_fma_f32 v3, v119, s74, -v173
	v_add_f32_e32 v2, v127, v2
	v_exp_f32_e32 v119, v3
	v_add_f32_e32 v2, v116, v2
	v_add_f32_e32 v2, v117, v2
	v_add_f32_e32 v2, v118, v2
	v_cmp_gt_f32_e32 vcc, v173, v171
	v_add_f32_e32 v156, v119, v2
	s_cbranch_vccz .LBB0_1405
	v_sub_f32_e32 v2, v171, v173
	v_exp_f32_e32 v112, v2
	v_mov_b32_e32 v2, v158
	v_fma_f32 v3, v159, v112, v156
	v_pk_mul_f32 v[102:103], v[98:99], v[112:113] op_sel_hi:[1,0]
	v_pk_mul_f32 v[100:101], v[96:97], v[112:113] op_sel_hi:[1,0]
	v_pk_mul_f32 v[106:107], v[94:95], v[112:113] op_sel_hi:[1,0]
	v_pk_mul_f32 v[104:105], v[92:93], v[112:113] op_sel_hi:[1,0]
	v_pk_mul_f32 v[110:111], v[90:91], v[112:113] op_sel_hi:[1,0]
	v_pk_mul_f32 v[108:109], v[88:89], v[112:113] op_sel_hi:[1,0]
	v_pk_mul_f32 v[114:115], v[86:87], v[112:113] op_sel_hi:[1,0]
	v_pk_mul_f32 v[112:113], v[84:85], v[112:113] op_sel_hi:[1,0]
	s_cbranch_execnz .LBB0_1394

.LBB0_1396:
	ds_read_b128 v[116:119], v155 offset:26624
	ds_read_b128 v[120:123], v155 offset:26688
	ds_read_b128 v[124:127], v155 offset:26752
	ds_read_b128 v[128:131], v155 offset:26816
	ds_read_b128 v[132:135], v155 offset:30976
	ds_read_b128 v[136:139], v155 offset:31040
	ds_read_b128 v[140:143], v155 offset:31104
	ds_read_b128 v[144:147], v155 offset:31168
	ds_read_b128 v[156:159], v155 offset:35328
	ds_read_b128 v[174:177], v155 offset:35392
	ds_read_b128 v[180:183], v155 offset:35456
	ds_read_b128 v[184:187], v155 offset:35520
	ds_read_b128 v[188:191], v155 offset:39680
	ds_read_b128 v[192:195], v155 offset:39744
	ds_read_b128 v[196:199], v155 offset:39808
	ds_read_b128 v[200:203], v155 offset:39872
	s_waitcnt lgkmcnt(14)
	v_mfma_f32_16x16x32_bf16 v[204:207], v[116:119], v[4:7], 0
	v_mfma_f32_16x16x32_bf16 v[116:119], v[116:119], v[20:23], 0
	v_mfma_f32_16x16x32_bf16 v[204:207], v[120:123], v[8:11], v[204:207]
	v_mfma_f32_16x16x32_bf16 v[116:119], v[120:123], v[24:27], v[116:119]
	s_waitcnt lgkmcnt(13)
	v_mfma_f32_16x16x32_bf16 v[120:123], v[124:127], v[12:15], v[204:207]
	s_waitcnt lgkmcnt(12)
	v_mfma_f32_16x16x32_bf16 v[204:207], v[128:131], v[16:19], v[120:123]
	s_waitcnt lgkmcnt(11)
	v_mfma_f32_16x16x32_bf16 v[120:123], v[132:135], v[4:7], 0
	s_waitcnt lgkmcnt(10)
	v_mfma_f32_16x16x32_bf16 v[120:123], v[136:139], v[8:11], v[120:123]
	s_nop 3
	v_mul_f32_e32 v0, 0x3e0293ee, v204
	v_mfma_f32_16x16x32_bf16 v[116:119], v[124:127], v[28:31], v[116:119]
	v_mfma_f32_16x16x32_bf16 v[124:127], v[132:135], v[20:23], 0
	s_waitcnt lgkmcnt(9)
	v_mfma_f32_16x16x32_bf16 v[120:123], v[140:143], v[12:15], v[120:123]
	v_mfma_f32_16x16x32_bf16 v[124:127], v[136:139], v[24:27], v[124:127]
	s_waitcnt lgkmcnt(8)
	v_mfma_f32_16x16x32_bf16 v[136:139], v[144:147], v[16:19], v[120:123]
	s_waitcnt lgkmcnt(7)
	v_mfma_f32_16x16x32_bf16 v[120:123], v[156:159], v[4:7], 0
	s_waitcnt lgkmcnt(6)
	v_mfma_f32_16x16x32_bf16 v[120:123], v[174:177], v[8:11], v[120:123]
	s_waitcnt lgkmcnt(5)
	v_mfma_f32_16x16x32_bf16 v[120:123], v[180:183], v[12:15], v[120:123]
	v_mfma_f32_16x16x32_bf16 v[124:127], v[140:143], v[28:31], v[124:127]
	s_waitcnt lgkmcnt(4)
	v_mfma_f32_16x16x32_bf16 v[140:143], v[184:187], v[16:19], v[120:123]
	s_waitcnt lgkmcnt(3)
	v_mfma_f32_16x16x32_bf16 v[120:123], v[188:191], v[4:7], 0
	v_mfma_f32_16x16x32_bf16 v[132:135], v[188:191], v[20:23], 0
	s_waitcnt lgkmcnt(2)
	v_mfma_f32_16x16x32_bf16 v[120:123], v[192:195], v[8:11], v[120:123]
	v_mfma_f32_16x16x32_bf16 v[132:135], v[192:195], v[24:27], v[132:135]
	v_mfma_f32_16x16x32_bf16 v[124:127], v[144:147], v[32:35], v[124:127]
	s_waitcnt lgkmcnt(1)
	v_mfma_f32_16x16x32_bf16 v[120:123], v[196:199], v[12:15], v[120:123]
	v_mfma_f32_16x16x32_bf16 v[144:147], v[196:199], v[28:31], v[132:135]
	s_waitcnt lgkmcnt(0)
	v_mfma_f32_16x16x32_bf16 v[132:135], v[200:203], v[16:19], v[120:123]
	v_mfma_f32_16x16x32_bf16 v[120:123], v[200:203], v[32:35], v[144:147]
	s_nop 4
	v_mul_f32_e32 v144, 0x3e0293ee, v205
	v_max3_f32 v0, v0, s82, v144
	v_mul_f32_e32 v144, 0x3e0293ee, v206
	v_mul_f32_e32 v145, 0x3e0293ee, v207
	v_max3_f32 v0, v0, v144, v145
	v_mul_f32_e32 v144, 0x3e0293ee, v136
	v_mul_f32_e32 v145, 0x3e0293ee, v137
	v_max3_f32 v0, v0, v144, v145
	v_mul_f32_e32 v144, 0x3e0293ee, v138
	v_mul_f32_e32 v145, 0x3e0293ee, v139
	v_max3_f32 v0, v0, v144, v145
	v_mul_f32_e32 v144, 0x3e0293ee, v140
	v_mul_f32_e32 v145, 0x3e0293ee, v141
	v_max3_f32 v0, v0, v144, v145
	v_mul_f32_e32 v144, 0x3e0293ee, v142
	v_mul_f32_e32 v145, 0x3e0293ee, v143
	v_max3_f32 v0, v0, v144, v145
	v_mul_f32_e32 v144, 0x3e0293ee, v132
	v_mul_f32_e32 v145, 0x3e0293ee, v133
	v_max3_f32 v0, v0, v144, v145
	v_mul_f32_e32 v144, 0x3e0293ee, v134
	v_mul_f32_e32 v145, 0x3e0293ee, v135
	v_max3_f32 v0, v0, v144, v145
	v_mov_b32_e32 v144, v0
	v_mfma_f32_16x16x32_bf16 v[116:119], v[128:131], v[32:35], v[116:119]
	s_waitcnt lgkmcnt(0)
	s_nop 1
	v_permlane16_swap_b32_e32 v144, v0
	v_max_f32_e32 v0, v0, v144
	v_mov_b32_e32 v144, v0
	v_mfma_f32_16x16x32_bf16 v[128:131], v[156:159], v[20:23], 0
	s_waitcnt lgkmcnt(0)
	s_nop 1
	v_permlane32_swap_b32_e32 v144, v0
	v_max3_f32 v170, v172, v0, v144
	v_fma_f32 v0, v204, s74, -v170
	v_exp_f32_e32 v0, v0
	v_fma_f32 v145, v205, s74, -v170
	v_mfma_f32_16x16x32_bf16 v[128:131], v[174:177], v[24:27], v[128:131]
	v_exp_f32_e32 v174, v145
	v_fma_f32 v145, v206, s74, -v170
	v_exp_f32_e32 v175, v145
	v_fma_f32 v145, v207, s74, -v170
	v_exp_f32_e32 v176, v145
	v_fma_f32 v136, v136, s74, -v170
	v_add_f32_e32 v144, 0, v0
	v_exp_f32_e32 v177, v136
	v_fma_f32 v137, v137, s74, -v170
	v_mfma_f32_16x16x32_bf16 v[128:131], v[180:183], v[28:31], v[128:131]
	v_add_f32_e32 v144, v174, v144
	v_exp_f32_e32 v180, v137
	v_fma_f32 v137, v138, s74, -v170
	v_add_f32_e32 v144, v175, v144
	v_exp_f32_e32 v181, v137
	v_fma_f32 v137, v139, s74, -v170
	v_add_f32_e32 v144, v176, v144
	v_exp_f32_e32 v183, v137
	v_fma_f32 v137, v140, s74, -v170
	v_add_f32_e32 v136, v177, v144
	v_exp_f32_e32 v182, v137
	v_fma_f32 v137, v141, s74, -v170
	v_mfma_f32_16x16x32_bf16 v[128:131], v[184:187], v[32:35], v[128:131]
	v_add_f32_e32 v136, v180, v136
	v_exp_f32_e32 v184, v137
	v_fma_f32 v137, v142, s74, -v170
	v_add_f32_e32 v136, v181, v136
	v_exp_f32_e32 v185, v137
	v_fma_f32 v137, v143, s74, -v170
	v_add_f32_e32 v136, v183, v136
	v_exp_f32_e32 v186, v137
	v_fma_f32 v132, v132, s74, -v170
	v_add_f32_e32 v136, v182, v136
	v_exp_f32_e32 v187, v132
	v_fma_f32 v133, v133, s74, -v170
	v_add_f32_e32 v136, v184, v136
	v_exp_f32_e32 v188, v133
	v_fma_f32 v133, v134, s74, -v170
	v_add_f32_e32 v136, v185, v136
	v_exp_f32_e32 v189, v133
	v_fma_f32 v133, v135, s74, -v170
	v_add_f32_e32 v136, v186, v136
	v_exp_f32_e32 v190, v133
	v_add_f32_e32 v132, v187, v136
	v_add_f32_e32 v132, v188, v132
	v_add_f32_e32 v132, v189, v132
	v_cmp_gt_f32_e32 vcc, v170, v172
	v_add_f32_e32 v156, v190, v132
	s_cbranch_vccz .LBB0_1406
	v_sub_f32_e32 v132, v172, v170
	v_exp_f32_e32 v144, v132
	v_mov_b32_e32 v159, v3
	v_fma_f32 v158, v2, v144, v156
	v_pk_mul_f32 v[134:135], v[102:103], v[144:145] op_sel_hi:[1,0]
	v_pk_mul_f32 v[132:133], v[100:101], v[144:145] op_sel_hi:[1,0]
	v_pk_mul_f32 v[138:139], v[106:107], v[144:145] op_sel_hi:[1,0]
	v_pk_mul_f32 v[136:137], v[104:105], v[144:145] op_sel_hi:[1,0]
	v_pk_mul_f32 v[142:143], v[110:111], v[144:145] op_sel_hi:[1,0]
	v_pk_mul_f32 v[140:141], v[108:109], v[144:145] op_sel_hi:[1,0]
	v_pk_mul_f32 v[146:147], v[114:115], v[144:145] op_sel_hi:[1,0]
	v_pk_mul_f32 v[144:145], v[112:113], v[144:145] op_sel_hi:[1,0]
	s_cbranch_execnz .LBB0_1399

.LBB0_1399:
	v_mul_f32_e32 v2, 0x3e0293ee, v116
	v_mul_f32_e32 v3, 0x3e0293ee, v117
	v_max3_f32 v2, v2, s82, v3
	v_mul_f32_e32 v3, 0x3e0293ee, v118
	v_mul_f32_e32 v100, 0x3e0293ee, v119
	v_max3_f32 v2, v2, v3, v100
	v_mul_f32_e32 v3, 0x3e0293ee, v124
	v_mul_f32_e32 v100, 0x3e0293ee, v125
	v_max3_f32 v2, v2, v3, v100
	v_mul_f32_e32 v3, 0x3e0293ee, v126
	v_mul_f32_e32 v100, 0x3e0293ee, v127
	v_max3_f32 v2, v2, v3, v100
	v_mul_f32_e32 v3, 0x3e0293ee, v128
	v_mul_f32_e32 v100, 0x3e0293ee, v129
	v_max3_f32 v2, v2, v3, v100
	v_mul_f32_e32 v3, 0x3e0293ee, v130
	v_mul_f32_e32 v100, 0x3e0293ee, v131
	v_max3_f32 v2, v2, v3, v100
	v_mul_f32_e32 v3, 0x3e0293ee, v120
	v_mul_f32_e32 v100, 0x3e0293ee, v121
	v_max3_f32 v2, v2, v3, v100
	v_mul_f32_e32 v3, 0x3e0293ee, v122
	v_mul_f32_e32 v100, 0x3e0293ee, v123
	v_max3_f32 v2, v2, v3, v100
	v_mov_b32_e32 v3, v2
	s_waitcnt lgkmcnt(0)
	s_nop 1
	v_permlane16_swap_b32_e32 v3, v2
	v_max_f32_e32 v2, v2, v3
	v_mov_b32_e32 v3, v2
	s_waitcnt lgkmcnt(0)
	s_nop 1
	v_permlane32_swap_b32_e32 v3, v2
	v_max3_f32 v171, v173, v2, v3
	v_fma_f32 v2, v116, s74, -v171
	v_exp_f32_e32 v2, v2
	v_fma_f32 v3, v117, s74, -v171
	v_exp_f32_e32 v3, v3
	v_fma_f32 v100, v118, s74, -v171
	v_exp_f32_e32 v116, v100
	v_fma_f32 v100, v119, s74, -v171
	v_exp_f32_e32 v117, v100
	v_fma_f32 v101, v124, s74, -v171
	v_add_f32_e32 v100, 0, v2
	v_exp_f32_e32 v118, v101
	v_fma_f32 v101, v125, s74, -v171
	v_add_f32_e32 v100, v3, v100
	v_exp_f32_e32 v124, v101
	v_fma_f32 v101, v126, s74, -v171
	v_add_f32_e32 v100, v116, v100
	v_exp_f32_e32 v126, v101
	v_fma_f32 v101, v127, s74, -v171
	v_add_f32_e32 v100, v117, v100
	v_exp_f32_e32 v172, v101
	v_fma_f32 v101, v128, s74, -v171
	v_add_f32_e32 v100, v118, v100
	v_exp_f32_e32 v119, v101
	v_fma_f32 v101, v129, s74, -v171
	v_add_f32_e32 v100, v124, v100
	v_exp_f32_e32 v125, v101
	v_fma_f32 v101, v130, s74, -v171
	v_add_f32_e32 v100, v126, v100
	v_exp_f32_e32 v127, v101
	v_fma_f32 v101, v131, s74, -v171
	v_add_f32_e32 v100, v172, v100
	v_exp_f32_e32 v128, v101
	v_fma_f32 v101, v120, s74, -v171
	v_add_f32_e32 v100, v119, v100
	v_exp_f32_e32 v120, v101
	v_fma_f32 v101, v121, s74, -v171
	v_add_f32_e32 v100, v125, v100
	v_exp_f32_e32 v121, v101
	v_fma_f32 v101, v122, s74, -v171
	v_add_f32_e32 v100, v127, v100
	v_exp_f32_e32 v122, v101
	v_fma_f32 v101, v123, s74, -v171
	v_add_f32_e32 v100, v128, v100
	v_exp_f32_e32 v123, v101
	v_add_f32_e32 v100, v120, v100
	v_add_f32_e32 v100, v121, v100
	v_add_f32_e32 v100, v122, v100
	v_cmp_gt_f32_e32 vcc, v171, v173
	v_add_f32_e32 v129, v123, v100
	s_cbranch_vccz .LBB0_1407
	v_sub_f32_e32 v100, v173, v171
	v_exp_f32_e32 v112, v100
	v_mov_b32_e32 v156, v158
	v_fma_f32 v157, v159, v112, v129
	v_pk_mul_f32 v[102:103], v[86:87], v[112:113] op_sel_hi:[1,0]
	v_pk_mul_f32 v[100:101], v[84:85], v[112:113] op_sel_hi:[1,0]
	v_pk_mul_f32 v[106:107], v[90:91], v[112:113] op_sel_hi:[1,0]
	v_pk_mul_f32 v[104:105], v[88:89], v[112:113] op_sel_hi:[1,0]
	v_pk_mul_f32 v[110:111], v[94:95], v[112:113] op_sel_hi:[1,0]
	v_pk_mul_f32 v[108:109], v[92:93], v[112:113] op_sel_hi:[1,0]
	v_pk_mul_f32 v[114:115], v[98:99], v[112:113] op_sel_hi:[1,0]
	v_pk_mul_f32 v[112:113], v[96:97], v[112:113] op_sel_hi:[1,0]
	s_cbranch_execnz .LBB0_1402

.LBB0_1462:
	s_andn2_b64 vcc, exec, s[0:1]
	s_cbranch_vccnz .LBB0_1375
	s_mov_b32 s13, s23
	s_branch .Lgla_new
	s_ashr_i32 s19, s23, 3
	s_lshl_b32 s8, s19, 1
	v_readlane_b32 s2, v255, 19
	s_or_b32 s8, s8, s2
	s_waitcnt vmcnt(8)
	v_mov_b32_e32 v50, v179
	s_and_b32 s13, s23, 1
	s_ashr_i32 s9, s8, 31
	s_lshl_b64 s[8:9], s[8:9], 3
	v_ashrrev_i32_e32 v46, 6, v50
	s_lshl_b32 s20, s13, 2
	v_and_b32_e32 v52, 15, v50
	s_bfe_u32 s10, s23, 0x20001
	s_or_b32 s8, s8, s20
	s_waitcnt vmcnt(1)
	v_lshlrev_b32_e32 v2, 5, v46
	v_readlane_b32 s40, v252, 8
	s_or_b32 s8, s8, s10
	v_lshlrev_b32_e32 v0, 2, v52
	v_readlane_b32 s44, v252, 12
	v_readlane_b32 s45, v252, 13
	v_ashrrev_i32_e32 v3, 31, v2
	v_bfe_u32 v38, v50, 4, 2
	v_lshl_add_u64 v[4:5], s[44:45], 0, v[0:1]
	v_lshlrev_b64 v[34:35], 2, v[2:3]
	s_lshl_b64 s[8:9], s[8:9], 15
	v_lshl_add_u64 v[22:23], v[4:5], 0, v[34:35]
	v_lshl_or_b32 v24, v38, 11, s8
	v_mov_b32_e32 v25, s9
	v_lshl_add_u64 v[30:31], v[22:23], 0, v[24:25]
	v_add_co_u32_e32 v10, vcc, s68, v30
	s_movk_i32 s2, 0x4000
	s_nop 0
	v_addc_co_u32_e32 v11, vcc, 0, v31, vcc
	s_waitcnt vmcnt(0)
	v_or_b32_e32 v6, 0x2000, v24
	v_mov_b32_e32 v7, s9
	v_add_co_u32_e32 v18, vcc, s2, v30
	s_mov_b64 s[0:1], 0
	v_lshl_add_u64 v[14:15], v[22:23], 0, v[6:7]
	v_addc_co_u32_e32 v19, vcc, 0, v31, vcc
	global_load_dword v26, v[30:31], off
	global_load_dword v27, v[30:31], off offset:512
	global_load_dword v28, v[30:31], off offset:1024
	global_load_dword v29, v[30:31], off offset:1536
	global_load_dword v5, v[30:31], off offset:1600
	global_load_dword v4, v[30:31], off offset:1088
	global_load_dword v3, v[30:31], off offset:576
	global_load_dword v2, v[30:31], off offset:64
	global_load_dword v6, v[14:15], off
	global_load_dword v7, v[10:11], off offset:512
	global_load_dword v8, v[10:11], off offset:1024
	global_load_dword v9, v[10:11], off offset:1536
	global_load_dword v13, v[10:11], off offset:1600
	global_load_dword v12, v[10:11], off offset:1088
	s_nop 0
	global_load_dword v11, v[10:11], off offset:576
	s_nop 0
	global_load_dword v10, v[14:15], off offset:64
	v_or_b32_e32 v14, 0x4000, v24
	v_mov_b32_e32 v15, s9
	v_or_b32_e32 v24, 0x6000, v24
	v_add_co_u32_e32 v30, vcc, s29, v30
	v_lshl_add_u64 v[32:33], v[22:23], 0, v[14:15]
	v_lshl_add_u64 v[36:37], v[22:23], 0, v[24:25]
	v_addc_co_u32_e32 v31, vcc, 0, v31, vcc
	global_load_dword v14, v[32:33], off
	global_load_dword v15, v[18:19], off offset:512
	global_load_dword v16, v[18:19], off offset:1024
	global_load_dword v17, v[18:19], off offset:1536
	global_load_dword v21, v[18:19], off offset:1600
	global_load_dword v20, v[18:19], off offset:1088
	s_nop 0
	global_load_dword v19, v[18:19], off offset:576
	s_nop 0
	global_load_dword v18, v[32:33], off offset:64
	global_load_dword v22, v[36:37], off
	global_load_dword v23, v[30:31], off offset:512
	global_load_dword v24, v[30:31], off offset:1024
	global_load_dword v25, v[30:31], off offset:1536
	s_nop 0
	global_load_dword v33, v[30:31], off offset:1600
	global_load_dword v32, v[30:31], off offset:1088
	s_nop 0
	global_load_dword v31, v[30:31], off offset:576
	s_nop 0
	global_load_dword v30, v[36:37], off offset:64
	s_lshl_b32 s8, s19, 12
	s_add_i32 s28, s8, 0x2000
	s_add_u32 s20, s90, s0
	s_addc_u32 s21, s91, s1
	s_ashr_i32 s23, s28, 6
	s_mul_i32 s0, s13, 0x3000000
	v_readlane_b32 s41, v252, 9
	s_add_u32 s40, s20, s0
	s_addc_u32 s41, s21, 0
	s_cmp_eq_u32 s13, 0
	s_cselect_b64 s[34:35], -1, 0
	s_add_u32 s8, s20, 0x2993d700
	s_addc_u32 s9, s21, 0
	s_add_u32 s0, s20, 0x2b13d700
	s_addc_u32 s1, s21, 0
	s_add_u32 s44, s20, 0x2c9fd700
	v_readlane_b32 s46, v252, 14
	s_addc_u32 s45, s21, 0
	v_readlane_b32 s47, v252, 15
	s_add_u32 s46, s20, 0x2c93d700
	v_and_b32_e32 v37, 63, v50
	s_addc_u32 s47, s21, 0
	v_or_b32_e32 v60, s28, v52
	s_lshl_b32 s28, s10, 9
	s_add_u32 s40, s40, s28
	v_lshlrev_b32_e32 v47, 7, v37
	v_lshlrev_b32_e32 v53, 11, v46
	v_and_b32_e32 v0, 48, v50
	s_addc_u32 s41, s41, 0
	v_add_u32_e32 v48, v53, v47
	v_lshlrev_b32_e32 v36, 2, v38
	v_lshl_add_u64 v[42:43], s[46:47], 0, v[0:1]
	v_lshl_add_u64 v[38:39], s[0:1], 0, v[0:1]
	v_lshl_add_u64 v[40:41], s[44:45], 0, v[0:1]
	v_lshl_add_u64 v[58:59], s[40:41], 0, v[0:1]
	v_lshlrev_b32_e32 v0, 12, v46
	s_movk_i32 s2, 0xf000
	v_add_u32_e32 v46, 0xfffff800, v48
	v_add3_u32 v44, v47, v0, s2
	v_ashrrev_i32_e32 v47, 31, v46
	v_ashrrev_i32_e32 v45, 31, v44
	v_lshl_add_u64 v[46:47], s[0:1], 0, v[46:47]
	v_cmp_gt_u32_e32 vcc, 64, v50
	v_cmp_gt_u32_e64 s[0:1], 2, v37
	v_lshlrev_b32_e32 v0, 7, v50
	v_lshl_or_b32 v56, v52, 6, v53
	v_readlane_b32 s42, v252, 10
	v_readlane_b32 s43, v252, 11
	v_lshl_add_u64 v[44:45], s[44:45], 0, v[44:45]
	v_ashrrev_i32_e32 v49, 31, v48
	s_and_b64 s[44:45], vcc, s[0:1]
	v_lshl_add_u64 v[50:51], s[46:47], 0, v[0:1]
	v_ashrrev_i32_e32 v57, 31, v56
	v_lshlrev_b32_e32 v0, 7, v52
	v_lshl_add_u64 v[34:35], v[58:59], 0, v[34:35]
	s_mov_b64 s[0:1], 0x2e1fd700
	s_mov_b32 s38, 63
	s_mov_b32 s19, 2
	v_cmp_lt_u32_e64 s[40:41], 15, v37
	v_cmp_lt_u32_e64 s[42:43], 31, v37
	v_lshl_add_u64 v[48:49], s[8:9], 0, v[48:49]
	v_lshl_add_u64 v[52:53], s[8:9], 0, v[0:1]
	v_lshl_add_u64 v[54:55], v[38:39], 0, v[0:1]
	v_lshl_add_u64 v[56:57], v[56:57], 1, v[40:41]
	v_lshl_add_u64 v[58:59], v[34:35], 0, s[0:1]
	v_mov_b32_e32 v61, 0
	v_lshlrev_b32_e32 v0, 1, v36
	v_readlane_b32 s48, v252, 16
	v_readlane_b32 s49, v252, 17
	v_readlane_b32 s50, v252, 18
	v_readlane_b32 s51, v252, 19
	v_readlane_b32 s52, v252, 20
	v_readlane_b32 s53, v252, 21
	v_readlane_b32 s54, v252, 22
	v_readlane_b32 s55, v252, 23
	s_and_b64 s[0:1], s[34:35], exec
	s_cselect_b32 s1, -1, 1
	s_mul_i32 s0, s1, 0x10000
	s_mul_i32 s8, s1, 0x800
	s_ashr_i32 s1, s1, 31
	v_mov_b32_e32 v154, s0
	v_mov_b32_e32 v157, s8
	v_mov_b32_e32 v155, s1

.Lgla_new:
	s_cmp_lt_u32 s13, 32
	s_cselect_b32 s56, 1, 0
	s_cselect_b32 s55, 64, 4
	s_sub_u32 s0, s13, 32
	s_cselect_b32 s0, s13, s0
	s_lshr_b32 s57, s0, 3
	s_bfe_u32 s58, s0, 0x20001
	s_and_b32 s59, s0, 1
	s_lshl_b32 s1, s57, 12
	s_add_u32 s1, s1, 8192
	s_lshl_b32 s2, s57, 8
	s_cmp_eq_u32 s56, 1
	s_cselect_b32 s1, s1, s2
	s_sub_u32 s2, s55, 1
	s_cmp_eq_u32 s59, 1
	s_cselect_b32 s2, s2, 0
	s_lshl_b32 s8, s2, 6
	s_add_u32 s8, s8, s1
	s_cmp_eq_u32 s59, 1
	s_cselect_b32 s51, -1, 0
	s_cselect_b32 s0, -1, 1
	s_mul_i32 s50, s0, 0x10000
	s_mul_i32 s52, s0, 0x800
	s_mul_i32 s53, s0, 0x20000
	s_mul_i32 s0, s59, 50331648
	s_lshl_b32 s2, s8, 11
	s_add_u32 s0, s0, s2
	s_lshl_b32 s2, s58, 9
	s_add_u32 s0, s0, s2
	s_add_u32 s0, s0, 0x2e1fd700
	s_add_u32 s48, s90, s0
	s_addc_u32 s49, s91, 0
	s_lshr_b32 s0, s8, 6
	s_lshl_b32 s0, s0, 2
	s_or_b32 s0, s0, s58
	s_lshl_b32 s2, s0, 14
	s_add_u32 s2, s2, 0x2c9fd700
	s_add_u32 s46, s90, s2
	s_addc_u32 s47, s91, 0
	s_lshl_b32 s0, s0, 1
	s_or_b32 s0, s0, s59
	s_lshl_b32 s2, s0, 13
	s_add_u32 s8, s2, 0x2993d700
	s_add_u32 s40, s90, s8
	s_addc_u32 s41, s91, 0
	s_add_u32 s8, s2, 0x2b13d700
	s_add_u32 s42, s90, s8
	s_addc_u32 s43, s91, 0
	s_lshl_b32 s2, s0, 8
	s_add_u32 s2, s2, 0x2c93d700
	s_add_u32 s44, s90, s2
	s_addc_u32 s45, s91, 0
	v_readlane_b32 s19, v255, 19
	s_lshl_b32 s0, s57, 1
	s_nop 0
	s_or_b32 s0, s0, s19
	s_lshl_b32 s0, s0, 1
	s_or_b32 s0, s0, s59
	s_lshl_b32 s0, s0, 2
	s_or_b32 s0, s0, s58
	s_lshl_b32 s0, s0, 15
	v_readlane_b32 s1, v252, 12
	v_readlane_b32 s2, v252, 13
	s_cmp_eq_u32 s56, 1
	s_cbranch_scc1 .Lgla_stb_in
	s_add_u32 s1, s88, 0x6000000
	s_addc_u32 s2, s89, 0
.Lgla_stb_in:
	s_add_u32 s60, s1, s0
	s_addc_u32 s61, s2, 0
	v_and_b32_e32 v244, 15, v179
	v_bfe_u32 v245, v179, 4, 2
	v_lshrrev_b32_e32 v246, 6, v179
	v_mul_u32_u24_e32 v247, 144, v244
	v_lshl_add_u32 v231, v245, 3, v247
	v_lshl_add_u32 v232, v245, 4, v247
	v_mul_u32_u24_e32 v247, 4608, v246
	v_add_u32_e32 v233, v232, v247
	v_add_u32_e32 v233, 18432, v233
	v_add_u32_e32 v232, 9216, v232
	v_lshlrev_b32_e32 v234, 4, v245
	v_lshlrev_b32_e32 v230, 4, v179
	v_lshrrev_b32_e32 v247, 3, v179
	v_and_b32_e32 v244, 7, v179
	v_mul_u32_u24_e32 v247, 144, v247
	v_lshl_add_u32 v235, v244, 4, v247
	v_add_u32_e32 v248, 36864, v235
	v_and_b32_e32 v244, 15, v179
	v_bfe_u32 v245, v179, 4, 2
	v_lshrrev_b32_e32 v246, 6, v179
	v_lshlrev_b32_e32 v244, 11, v244
	v_lshl_add_u32 v244, v246, 7, v244
	v_lshl_add_u32 v236, v245, 4, v244
	v_add_u32_e32 v237, 0x8000, v236
	v_add_u32_e32 v238, 0x10000, v236
	v_add_u32_e32 v239, 0x18000, v236
	v_and_b32_e32 v244, 15, v179
	v_lshlrev_b32_e32 v245, 11, v245
	v_lshl_add_u32 v245, v246, 7, v245
	v_lshl_add_u32 v240, v244, 2, v245
	v_add_u32_e32 v241, 0x2000, v240
	v_add_u32_e32 v242, 0x4000, v240
	v_add_u32_e32 v243, 0x6000, v240
	s_cmp_eq_u32 s56, 1
	s_cbranch_scc0 .Lgla_zero
	global_load_dword v2, v240, s[60:61] offset:0
	global_load_dword v3, v240, s[60:61] offset:512
	global_load_dword v4, v240, s[60:61] offset:1024
	global_load_dword v5, v240, s[60:61] offset:1536
	global_load_dword v6, v240, s[60:61] offset:64
	global_load_dword v7, v240, s[60:61] offset:576
	global_load_dword v8, v240, s[60:61] offset:1088
	global_load_dword v9, v240, s[60:61] offset:1600
	global_load_dword v10, v241, s[60:61] offset:0
	global_load_dword v11, v241, s[60:61] offset:512
	global_load_dword v12, v241, s[60:61] offset:1024
	global_load_dword v13, v241, s[60:61] offset:1536
	global_load_dword v14, v241, s[60:61] offset:64
	global_load_dword v15, v241, s[60:61] offset:576
	global_load_dword v16, v241, s[60:61] offset:1088
	global_load_dword v17, v241, s[60:61] offset:1600
	global_load_dword v18, v242, s[60:61] offset:0
	global_load_dword v19, v242, s[60:61] offset:512
	global_load_dword v20, v242, s[60:61] offset:1024
	global_load_dword v21, v242, s[60:61] offset:1536
	global_load_dword v22, v242, s[60:61] offset:64
	global_load_dword v23, v242, s[60:61] offset:576
	global_load_dword v24, v242, s[60:61] offset:1088
	global_load_dword v25, v242, s[60:61] offset:1600
	global_load_dword v26, v243, s[60:61] offset:0
	global_load_dword v27, v243, s[60:61] offset:512
	global_load_dword v28, v243, s[60:61] offset:1024
	global_load_dword v29, v243, s[60:61] offset:1536
	global_load_dword v30, v243, s[60:61] offset:64
	global_load_dword v31, v243, s[60:61] offset:576
	global_load_dword v32, v243, s[60:61] offset:1088
	global_load_dword v33, v243, s[60:61] offset:1600
	s_branch .Lgla_start
.Lgla_zero:
	v_mov_b32_e32 v2, 0
	v_mov_b32_e32 v3, 0
	v_mov_b32_e32 v4, 0
	v_mov_b32_e32 v5, 0
	v_mov_b32_e32 v6, 0
	v_mov_b32_e32 v7, 0
	v_mov_b32_e32 v8, 0
	v_mov_b32_e32 v9, 0
	v_mov_b32_e32 v10, 0
	v_mov_b32_e32 v11, 0
	v_mov_b32_e32 v12, 0
	v_mov_b32_e32 v13, 0
	v_mov_b32_e32 v14, 0
	v_mov_b32_e32 v15, 0
	v_mov_b32_e32 v16, 0
	v_mov_b32_e32 v17, 0
	v_mov_b32_e32 v18, 0
	v_mov_b32_e32 v19, 0
	v_mov_b32_e32 v20, 0
	v_mov_b32_e32 v21, 0
	v_mov_b32_e32 v22, 0
	v_mov_b32_e32 v23, 0
	v_mov_b32_e32 v24, 0
	v_mov_b32_e32 v25, 0
	v_mov_b32_e32 v26, 0
	v_mov_b32_e32 v27, 0
	v_mov_b32_e32 v28, 0
	v_mov_b32_e32 v29, 0
	v_mov_b32_e32 v30, 0
	v_mov_b32_e32 v31, 0
	v_mov_b32_e32 v32, 0
	v_mov_b32_e32 v33, 0
.Lgla_start:
	s_add_u32 s20, s40, 0x1000
	s_addc_u32 s21, s41, 0
	global_load_dwordx4 v[180:183], v230, s[40:41]
	global_load_dwordx4 v[184:187], v230, s[20:21]
	s_add_u32 s34, s42, 0x1000
	s_addc_u32 s35, s43, 0
	global_load_dwordx4 v[188:191], v230, s[42:43]
	global_load_dwordx4 v[192:195], v230, s[34:35]
	global_load_dwordx4 v[196:199], v230, s[46:47]
	s_add_u32 s20, s46, 0x1000
	s_addc_u32 s21, s47, 0
	global_load_dwordx4 v[200:203], v230, s[20:21]
	s_add_u32 s34, s46, 0x2000
	s_addc_u32 s35, s47, 0
	global_load_dwordx4 v[204:207], v230, s[34:35]
	s_add_u32 s20, s46, 0x3000
	s_addc_u32 s21, s47, 0
	global_load_dwordx4 v[226:229], v230, s[20:21]
	s_add_u32 s40, s40, s50
	s_addc_u32 s41, s41, s51
	s_add_u32 s42, s42, s50
	s_addc_u32 s43, s43, s51
	s_add_u32 s46, s46, s50
	s_addc_u32 s47, s47, s51
	global_load_dwordx4 v[114:117], v234, s[44:45]
	global_load_dwordx4 v[118:121], v234, s[44:45] offset:64
	global_load_dwordx4 v[122:125], v234, s[44:45] offset:128
	global_load_dwordx4 v[126:129], v234, s[44:45] offset:192
	s_add_u32 s44, s44, s52
	s_addc_u32 s45, s45, s51
	s_waitcnt vmcnt(0)
	v_cvt_pk_bf16_f32 v130, v2, v3
	v_cvt_pk_bf16_f32 v131, v4, v5
	v_cvt_pk_bf16_f32 v132, v10, v11
	v_cvt_pk_bf16_f32 v133, v12, v13
	v_cvt_pk_bf16_f32 v134, v6, v7
	v_cvt_pk_bf16_f32 v135, v8, v9
	v_cvt_pk_bf16_f32 v136, v14, v15
	v_cvt_pk_bf16_f32 v137, v16, v17
	v_cvt_pk_bf16_f32 v138, v18, v19
	v_cvt_pk_bf16_f32 v139, v20, v21
	v_cvt_pk_bf16_f32 v140, v26, v27
	v_cvt_pk_bf16_f32 v141, v28, v29
	v_cvt_pk_bf16_f32 v142, v22, v23
	v_cvt_pk_bf16_f32 v143, v24, v25
	v_cvt_pk_bf16_f32 v144, v30, v31
	v_cvt_pk_bf16_f32 v145, v32, v33
	s_mov_b32 s54, 0
.Lgla_loop:
	s_waitcnt vmcnt(12)
	ds_write_b128 v235, v[180:183] offset:0
	ds_write_b128 v235, v[184:187] offset:4608
	ds_write_b128 v235, v[188:191] offset:9216
	ds_write_b128 v235, v[192:195] offset:13824
	ds_write_b128 v235, v[196:199] offset:18432
	ds_write_b128 v235, v[200:203] offset:23040
	ds_write_b128 v235, v[204:207] offset:27648
	ds_write_b128 v235, v[226:229] offset:32256
	s_waitcnt lgkmcnt(0)
	s_barrier
	s_add_u32 s20, s40, 0x1000
	s_addc_u32 s21, s41, 0
	global_load_dwordx4 v[180:183], v230, s[40:41]
	global_load_dwordx4 v[184:187], v230, s[20:21]
	s_add_u32 s34, s42, 0x1000
	s_addc_u32 s35, s43, 0
	global_load_dwordx4 v[188:191], v230, s[42:43]
	global_load_dwordx4 v[192:195], v230, s[34:35]
	global_load_dwordx4 v[196:199], v230, s[46:47]
	s_add_u32 s20, s46, 0x1000
	s_addc_u32 s21, s47, 0
	global_load_dwordx4 v[200:203], v230, s[20:21]
	s_add_u32 s34, s46, 0x2000
	s_addc_u32 s35, s47, 0
	global_load_dwordx4 v[204:207], v230, s[34:35]
	s_add_u32 s20, s46, 0x3000
	s_addc_u32 s21, s47, 0
	global_load_dwordx4 v[226:229], v230, s[20:21]
	s_add_u32 s40, s40, s50
	s_addc_u32 s41, s41, s51
	s_add_u32 s42, s42, s50
	s_addc_u32 s43, s43, s51
	s_add_u32 s46, s46, s50
	s_addc_u32 s47, s47, s51
	ds_read_b64 v[34:35], v231 offset:0
	ds_read_b64 v[36:37], v231 offset:32
	ds_read_b64 v[38:39], v231 offset:64
	ds_read_b64 v[40:41], v231 offset:96
	ds_read_b64 v[42:43], v231 offset:2304
	ds_read_b64 v[44:45], v231 offset:2336
	ds_read_b64 v[46:47], v231 offset:2368
	ds_read_b64 v[48:49], v231 offset:2400
	ds_read_b64 v[50:51], v231 offset:4608
	ds_read_b64 v[52:53], v231 offset:4640
	ds_read_b64 v[54:55], v231 offset:4672
	ds_read_b64 v[56:57], v231 offset:4704
	ds_read_b64 v[58:59], v231 offset:6912
	ds_read_b64 v[60:61], v231 offset:6944
	ds_read_b64 v[62:63], v231 offset:6976
	ds_read_b64 v[64:65], v231 offset:7008
	ds_read_b128 v[66:69], v232 offset:0
	ds_read_b128 v[70:73], v232 offset:64
	ds_read_b128 v[74:77], v232 offset:2304
	ds_read_b128 v[78:81], v232 offset:2368
	ds_read_b128 v[82:85], v232 offset:4608
	ds_read_b128 v[86:89], v232 offset:4672
	ds_read_b128 v[90:93], v232 offset:6912
	ds_read_b128 v[94:97], v232 offset:6976
	ds_read_b128 v[98:101], v233 offset:0
	ds_read_b128 v[102:105], v233 offset:64
	ds_read_b128 v[106:109], v233 offset:2304
	ds_read_b128 v[110:113], v233 offset:2368
	s_waitcnt lgkmcnt(12)
	v_mfma_f32_16x16x32_bf16 v[146:149], v[130:133], v[34:37], 0
	v_mfma_f32_16x16x32_bf16 v[150:153], v[134:137], v[34:37], 0
	v_mfma_f32_16x16x32_bf16 v[154:157], v[130:133], v[42:45], 0
	v_mfma_f32_16x16x32_bf16 v[158:161], v[134:137], v[42:45], 0
	v_mfma_f32_16x16x32_bf16 v[162:165], v[130:133], v[50:53], 0
	v_mfma_f32_16x16x32_bf16 v[166:169], v[134:137], v[50:53], 0
	v_mfma_f32_16x16x32_bf16 v[170:173], v[130:133], v[58:61], 0
	v_mfma_f32_16x16x32_bf16 v[174:177], v[134:137], v[58:61], 0
	v_mfma_f32_16x16x32_bf16 v[146:149], v[138:141], v[38:41], v[146:149]
	v_mfma_f32_16x16x32_bf16 v[150:153], v[142:145], v[38:41], v[150:153]
	v_mfma_f32_16x16x32_bf16 v[154:157], v[138:141], v[46:49], v[154:157]
	v_mfma_f32_16x16x32_bf16 v[158:161], v[142:145], v[46:49], v[158:161]
	v_mfma_f32_16x16x32_bf16 v[162:165], v[138:141], v[54:57], v[162:165]
	v_mfma_f32_16x16x32_bf16 v[166:169], v[142:145], v[54:57], v[166:169]
	v_mfma_f32_16x16x32_bf16 v[170:173], v[138:141], v[62:65], v[170:173]
	v_mfma_f32_16x16x32_bf16 v[174:177], v[142:145], v[62:65], v[174:177]
	s_waitcnt vmcnt(8)
	v_mul_f32_e32 v2, v2, v114
	v_mul_f32_e32 v3, v3, v115
	v_mul_f32_e32 v4, v4, v116
	v_mul_f32_e32 v5, v5, v117
	v_mul_f32_e32 v6, v6, v114
	v_mul_f32_e32 v7, v7, v115
	v_mul_f32_e32 v8, v8, v116
	v_mul_f32_e32 v9, v9, v117
	v_mul_f32_e32 v10, v10, v118
	v_mul_f32_e32 v11, v11, v119
	v_mul_f32_e32 v12, v12, v120
	v_mul_f32_e32 v13, v13, v121
	v_mul_f32_e32 v14, v14, v118
	v_mul_f32_e32 v15, v15, v119
	v_mul_f32_e32 v16, v16, v120
	v_mul_f32_e32 v17, v17, v121
	v_mul_f32_e32 v18, v18, v122
	v_mul_f32_e32 v19, v19, v123
	v_mul_f32_e32 v20, v20, v124
	v_mul_f32_e32 v21, v21, v125
	v_mul_f32_e32 v22, v22, v122
	v_mul_f32_e32 v23, v23, v123
	v_mul_f32_e32 v24, v24, v124
	v_mul_f32_e32 v25, v25, v125
	v_mul_f32_e32 v26, v26, v126
	v_mul_f32_e32 v27, v27, v127
	v_mul_f32_e32 v28, v28, v128
	v_mul_f32_e32 v29, v29, v129
	v_mul_f32_e32 v30, v30, v126
	v_mul_f32_e32 v31, v31, v127
	v_mul_f32_e32 v32, v32, v128
	v_mul_f32_e32 v33, v33, v129
	s_waitcnt lgkmcnt(0)
	global_store_dwordx4 v236, v[146:149], s[48:49]
	global_store_dwordx4 v236, v[150:153], s[48:49] offset:64
	global_store_dwordx4 v237, v[154:157], s[48:49]
	global_store_dwordx4 v237, v[158:161], s[48:49] offset:64
	global_store_dwordx4 v238, v[162:165], s[48:49]
	global_store_dwordx4 v238, v[166:169], s[48:49] offset:64
	global_store_dwordx4 v239, v[170:173], s[48:49]
	global_store_dwordx4 v239, v[174:177], s[48:49] offset:64
	s_add_u32 s48, s48, s53
	s_addc_u32 s49, s49, s51
	v_mfma_f32_16x16x32_bf16 v[2:5], v[66:69], v[98:101], v[2:5]
	v_mfma_f32_16x16x32_bf16 v[6:9], v[66:69], v[106:109], v[6:9]
	v_mfma_f32_16x16x32_bf16 v[10:13], v[74:77], v[98:101], v[10:13]
	v_mfma_f32_16x16x32_bf16 v[14:17], v[74:77], v[106:109], v[14:17]
	v_mfma_f32_16x16x32_bf16 v[18:21], v[82:85], v[98:101], v[18:21]
	v_mfma_f32_16x16x32_bf16 v[22:25], v[82:85], v[106:109], v[22:25]
	v_mfma_f32_16x16x32_bf16 v[26:29], v[90:93], v[98:101], v[26:29]
	v_mfma_f32_16x16x32_bf16 v[30:33], v[90:93], v[106:109], v[30:33]
	v_mfma_f32_16x16x32_bf16 v[2:5], v[70:73], v[102:105], v[2:5]
	v_mfma_f32_16x16x32_bf16 v[6:9], v[70:73], v[110:113], v[6:9]
	v_mfma_f32_16x16x32_bf16 v[10:13], v[78:81], v[102:105], v[10:13]
	v_mfma_f32_16x16x32_bf16 v[14:17], v[78:81], v[110:113], v[14:17]
	v_mfma_f32_16x16x32_bf16 v[18:21], v[86:89], v[102:105], v[18:21]
	v_mfma_f32_16x16x32_bf16 v[22:25], v[86:89], v[110:113], v[22:25]
	v_mfma_f32_16x16x32_bf16 v[26:29], v[94:97], v[102:105], v[26:29]
	v_mfma_f32_16x16x32_bf16 v[30:33], v[94:97], v[110:113], v[30:33]
	global_load_dwordx4 v[114:117], v234, s[44:45]
	global_load_dwordx4 v[118:121], v234, s[44:45] offset:64
	global_load_dwordx4 v[122:125], v234, s[44:45] offset:128
	global_load_dwordx4 v[126:129], v234, s[44:45] offset:192
	s_add_u32 s44, s44, s52
	s_addc_u32 s45, s45, s51
	s_nop 7
	s_nop 1
	v_cvt_pk_bf16_f32 v130, v2, v3
	v_cvt_pk_bf16_f32 v131, v4, v5
	v_cvt_pk_bf16_f32 v132, v10, v11
	v_cvt_pk_bf16_f32 v133, v12, v13
	v_cvt_pk_bf16_f32 v134, v6, v7
	v_cvt_pk_bf16_f32 v135, v8, v9
	v_cvt_pk_bf16_f32 v136, v14, v15
	v_cvt_pk_bf16_f32 v137, v16, v17
	v_cvt_pk_bf16_f32 v138, v18, v19
	v_cvt_pk_bf16_f32 v139, v20, v21
	v_cvt_pk_bf16_f32 v140, v26, v27
	v_cvt_pk_bf16_f32 v141, v28, v29
	v_cvt_pk_bf16_f32 v142, v22, v23
	v_cvt_pk_bf16_f32 v143, v24, v25
	v_cvt_pk_bf16_f32 v144, v30, v31
	v_cvt_pk_bf16_f32 v145, v32, v33
	s_add_u32 s54, s54, 1
	s_waitcnt vmcnt(12)
	ds_write_b128 v248, v[180:183] offset:0
	ds_write_b128 v248, v[184:187] offset:4608
	ds_write_b128 v248, v[188:191] offset:9216
	ds_write_b128 v248, v[192:195] offset:13824
	ds_write_b128 v248, v[196:199] offset:18432
	ds_write_b128 v248, v[200:203] offset:23040
	ds_write_b128 v248, v[204:207] offset:27648
	ds_write_b128 v248, v[226:229] offset:32256
	s_waitcnt lgkmcnt(0)
	s_barrier
	s_add_u32 s20, s40, 0x1000
	s_addc_u32 s21, s41, 0
	global_load_dwordx4 v[180:183], v230, s[40:41]
	global_load_dwordx4 v[184:187], v230, s[20:21]
	s_add_u32 s34, s42, 0x1000
	s_addc_u32 s35, s43, 0
	global_load_dwordx4 v[188:191], v230, s[42:43]
	global_load_dwordx4 v[192:195], v230, s[34:35]
	global_load_dwordx4 v[196:199], v230, s[46:47]
	s_add_u32 s20, s46, 0x1000
	s_addc_u32 s21, s47, 0
	global_load_dwordx4 v[200:203], v230, s[20:21]
	s_add_u32 s34, s46, 0x2000
	s_addc_u32 s35, s47, 0
	global_load_dwordx4 v[204:207], v230, s[34:35]
	s_add_u32 s20, s46, 0x3000
	s_addc_u32 s21, s47, 0
	global_load_dwordx4 v[226:229], v230, s[20:21]
	s_add_u32 s40, s40, s50
	s_addc_u32 s41, s41, s51
	s_add_u32 s42, s42, s50
	s_addc_u32 s43, s43, s51
	s_add_u32 s46, s46, s50
	s_addc_u32 s47, s47, s51
	ds_read_b64 v[34:35], v231 offset:36864
	ds_read_b64 v[36:37], v231 offset:36896
	ds_read_b64 v[38:39], v231 offset:36928
	ds_read_b64 v[40:41], v231 offset:36960
	ds_read_b64 v[42:43], v231 offset:39168
	ds_read_b64 v[44:45], v231 offset:39200
	ds_read_b64 v[46:47], v231 offset:39232
	ds_read_b64 v[48:49], v231 offset:39264
	ds_read_b64 v[50:51], v231 offset:41472
	ds_read_b64 v[52:53], v231 offset:41504
	ds_read_b64 v[54:55], v231 offset:41536
	ds_read_b64 v[56:57], v231 offset:41568
	ds_read_b64 v[58:59], v231 offset:43776
	ds_read_b64 v[60:61], v231 offset:43808
	ds_read_b64 v[62:63], v231 offset:43840
	ds_read_b64 v[64:65], v231 offset:43872
	ds_read_b128 v[66:69], v232 offset:36864
	ds_read_b128 v[70:73], v232 offset:36928
	ds_read_b128 v[74:77], v232 offset:39168
	ds_read_b128 v[78:81], v232 offset:39232
	ds_read_b128 v[82:85], v232 offset:41472
	ds_read_b128 v[86:89], v232 offset:41536
	ds_read_b128 v[90:93], v232 offset:43776
	ds_read_b128 v[94:97], v232 offset:43840
	ds_read_b128 v[98:101], v233 offset:36864
	ds_read_b128 v[102:105], v233 offset:36928
	ds_read_b128 v[106:109], v233 offset:39168
	ds_read_b128 v[110:113], v233 offset:39232
	s_waitcnt lgkmcnt(12)
	v_mfma_f32_16x16x32_bf16 v[146:149], v[130:133], v[34:37], 0
	v_mfma_f32_16x16x32_bf16 v[150:153], v[134:137], v[34:37], 0
	v_mfma_f32_16x16x32_bf16 v[154:157], v[130:133], v[42:45], 0
	v_mfma_f32_16x16x32_bf16 v[158:161], v[134:137], v[42:45], 0
	v_mfma_f32_16x16x32_bf16 v[162:165], v[130:133], v[50:53], 0
	v_mfma_f32_16x16x32_bf16 v[166:169], v[134:137], v[50:53], 0
	v_mfma_f32_16x16x32_bf16 v[170:173], v[130:133], v[58:61], 0
	v_mfma_f32_16x16x32_bf16 v[174:177], v[134:137], v[58:61], 0
	v_mfma_f32_16x16x32_bf16 v[146:149], v[138:141], v[38:41], v[146:149]
	v_mfma_f32_16x16x32_bf16 v[150:153], v[142:145], v[38:41], v[150:153]
	v_mfma_f32_16x16x32_bf16 v[154:157], v[138:141], v[46:49], v[154:157]
	v_mfma_f32_16x16x32_bf16 v[158:161], v[142:145], v[46:49], v[158:161]
	v_mfma_f32_16x16x32_bf16 v[162:165], v[138:141], v[54:57], v[162:165]
	v_mfma_f32_16x16x32_bf16 v[166:169], v[142:145], v[54:57], v[166:169]
	v_mfma_f32_16x16x32_bf16 v[170:173], v[138:141], v[62:65], v[170:173]
	v_mfma_f32_16x16x32_bf16 v[174:177], v[142:145], v[62:65], v[174:177]
	s_waitcnt vmcnt(8)
	v_mul_f32_e32 v2, v2, v114
	v_mul_f32_e32 v3, v3, v115
	v_mul_f32_e32 v4, v4, v116
	v_mul_f32_e32 v5, v5, v117
	v_mul_f32_e32 v6, v6, v114
	v_mul_f32_e32 v7, v7, v115
	v_mul_f32_e32 v8, v8, v116
	v_mul_f32_e32 v9, v9, v117
	v_mul_f32_e32 v10, v10, v118
	v_mul_f32_e32 v11, v11, v119
	v_mul_f32_e32 v12, v12, v120
	v_mul_f32_e32 v13, v13, v121
	v_mul_f32_e32 v14, v14, v118
	v_mul_f32_e32 v15, v15, v119
	v_mul_f32_e32 v16, v16, v120
	v_mul_f32_e32 v17, v17, v121
	v_mul_f32_e32 v18, v18, v122
	v_mul_f32_e32 v19, v19, v123
	v_mul_f32_e32 v20, v20, v124
	v_mul_f32_e32 v21, v21, v125
	v_mul_f32_e32 v22, v22, v122
	v_mul_f32_e32 v23, v23, v123
	v_mul_f32_e32 v24, v24, v124
	v_mul_f32_e32 v25, v25, v125
	v_mul_f32_e32 v26, v26, v126
	v_mul_f32_e32 v27, v27, v127
	v_mul_f32_e32 v28, v28, v128
	v_mul_f32_e32 v29, v29, v129
	v_mul_f32_e32 v30, v30, v126
	v_mul_f32_e32 v31, v31, v127
	v_mul_f32_e32 v32, v32, v128
	v_mul_f32_e32 v33, v33, v129
	s_waitcnt lgkmcnt(0)
	global_store_dwordx4 v236, v[146:149], s[48:49]
	global_store_dwordx4 v236, v[150:153], s[48:49] offset:64
	global_store_dwordx4 v237, v[154:157], s[48:49]
	global_store_dwordx4 v237, v[158:161], s[48:49] offset:64
	global_store_dwordx4 v238, v[162:165], s[48:49]
	global_store_dwordx4 v238, v[166:169], s[48:49] offset:64
	global_store_dwordx4 v239, v[170:173], s[48:49]
	global_store_dwordx4 v239, v[174:177], s[48:49] offset:64
	s_add_u32 s48, s48, s53
	s_addc_u32 s49, s49, s51
	v_mfma_f32_16x16x32_bf16 v[2:5], v[66:69], v[98:101], v[2:5]
	v_mfma_f32_16x16x32_bf16 v[6:9], v[66:69], v[106:109], v[6:9]
	v_mfma_f32_16x16x32_bf16 v[10:13], v[74:77], v[98:101], v[10:13]
	v_mfma_f32_16x16x32_bf16 v[14:17], v[74:77], v[106:109], v[14:17]
	v_mfma_f32_16x16x32_bf16 v[18:21], v[82:85], v[98:101], v[18:21]
	v_mfma_f32_16x16x32_bf16 v[22:25], v[82:85], v[106:109], v[22:25]
	v_mfma_f32_16x16x32_bf16 v[26:29], v[90:93], v[98:101], v[26:29]
	v_mfma_f32_16x16x32_bf16 v[30:33], v[90:93], v[106:109], v[30:33]
	v_mfma_f32_16x16x32_bf16 v[2:5], v[70:73], v[102:105], v[2:5]
	v_mfma_f32_16x16x32_bf16 v[6:9], v[70:73], v[110:113], v[6:9]
	v_mfma_f32_16x16x32_bf16 v[10:13], v[78:81], v[102:105], v[10:13]
	v_mfma_f32_16x16x32_bf16 v[14:17], v[78:81], v[110:113], v[14:17]
	v_mfma_f32_16x16x32_bf16 v[18:21], v[86:89], v[102:105], v[18:21]
	v_mfma_f32_16x16x32_bf16 v[22:25], v[86:89], v[110:113], v[22:25]
	v_mfma_f32_16x16x32_bf16 v[26:29], v[94:97], v[102:105], v[26:29]
	v_mfma_f32_16x16x32_bf16 v[30:33], v[94:97], v[110:113], v[30:33]
	global_load_dwordx4 v[114:117], v234, s[44:45]
	global_load_dwordx4 v[118:121], v234, s[44:45] offset:64
	global_load_dwordx4 v[122:125], v234, s[44:45] offset:128
	global_load_dwordx4 v[126:129], v234, s[44:45] offset:192
	s_add_u32 s44, s44, s52
	s_addc_u32 s45, s45, s51
	s_nop 7
	s_nop 1
	v_cvt_pk_bf16_f32 v130, v2, v3
	v_cvt_pk_bf16_f32 v131, v4, v5
	v_cvt_pk_bf16_f32 v132, v10, v11
	v_cvt_pk_bf16_f32 v133, v12, v13
	v_cvt_pk_bf16_f32 v134, v6, v7
	v_cvt_pk_bf16_f32 v135, v8, v9
	v_cvt_pk_bf16_f32 v136, v14, v15
	v_cvt_pk_bf16_f32 v137, v16, v17
	v_cvt_pk_bf16_f32 v138, v18, v19
	v_cvt_pk_bf16_f32 v139, v20, v21
	v_cvt_pk_bf16_f32 v140, v26, v27
	v_cvt_pk_bf16_f32 v141, v28, v29
	v_cvt_pk_bf16_f32 v142, v22, v23
	v_cvt_pk_bf16_f32 v143, v24, v25
	v_cvt_pk_bf16_f32 v144, v30, v31
	v_cvt_pk_bf16_f32 v145, v32, v33
	s_add_u32 s54, s54, 1
	s_cmp_lt_u32 s54, s55
	s_cbranch_scc1 .Lgla_loop
	s_waitcnt vmcnt(0)
	s_cmp_eq_u32 s56, 1
	s_cbranch_scc1 .Lgla_done
	global_store_dword v240, v2, s[60:61] offset:0
	global_store_dword v240, v3, s[60:61] offset:512
	global_store_dword v240, v4, s[60:61] offset:1024
	global_store_dword v240, v5, s[60:61] offset:1536
	global_store_dword v240, v6, s[60:61] offset:64
	global_store_dword v240, v7, s[60:61] offset:576
	global_store_dword v240, v8, s[60:61] offset:1088
	global_store_dword v240, v9, s[60:61] offset:1600
	global_store_dword v241, v10, s[60:61] offset:0
	global_store_dword v241, v11, s[60:61] offset:512
	global_store_dword v241, v12, s[60:61] offset:1024
	global_store_dword v241, v13, s[60:61] offset:1536
	global_store_dword v241, v14, s[60:61] offset:64
	global_store_dword v241, v15, s[60:61] offset:576
	global_store_dword v241, v16, s[60:61] offset:1088
	global_store_dword v241, v17, s[60:61] offset:1600
	global_store_dword v242, v18, s[60:61] offset:0
	global_store_dword v242, v19, s[60:61] offset:512
	global_store_dword v242, v20, s[60:61] offset:1024
	global_store_dword v242, v21, s[60:61] offset:1536
	global_store_dword v242, v22, s[60:61] offset:64
	global_store_dword v242, v23, s[60:61] offset:576
	global_store_dword v242, v24, s[60:61] offset:1088
	global_store_dword v242, v25, s[60:61] offset:1600
	global_store_dword v243, v26, s[60:61] offset:0
	global_store_dword v243, v27, s[60:61] offset:512
	global_store_dword v243, v28, s[60:61] offset:1024
	global_store_dword v243, v29, s[60:61] offset:1536
	global_store_dword v243, v30, s[60:61] offset:64
	global_store_dword v243, v31, s[60:61] offset:576
	global_store_dword v243, v32, s[60:61] offset:1088
	global_store_dword v243, v33, s[60:61] offset:1600
	s_waitcnt vmcnt(0)
.Lgla_done:
	s_barrier
	s_branch .LBB0_1375
